# residual epilogue (FFN1-out): f32 Y stores write full 32B sectors via permlane16 lane exchange
# baseline (speedup 1.0000x reference)
; __device__ __forceinline__ float xsum16(float v) { const auto r = __builtin_amdgcn_permlane16_swap(__float_as_uint(v), __float_as_uint(v), false, false); return __uint_as_float(r[0]) + __uint_as_float(r[1]); }
; __device__ __forceinline__ float xsum32(float v) { const auto r = __builtin_amdgcn_permlane32_swap(__float_as_uint(v), __float_as_uint(v), false, false); return __uint_as_float(r[0]) + __uint_as_float(r[1]); }
; __device__ __forceinline__ void row_stats4(const float* st, int rowb, int fq, float (&mu)[4], float (&rs)[4]) {
;     ...
;     for (int m = 0; m < 4; ++m) { const f32x4* p = (const f32x4*)(st + (size_t)(rowb + m * 16) * 32 + fq * 8); a[m] = p[0]; b[m] = p[1]; }
; #pragma unroll
;     for (int m = 0; m < 4; ++m) { float s1 = (a[m][0] + a[m][2]) + (b[m][0] + b[m][2]), s2 = (a[m][1] + a[m][3]) + (b[m][1] + b[m][3]);
;         s1 = xsum32(xsum16(s1)); s2 = xsum32(xsum16(s2));
;         const float mm = s1 * (1.0f / 1024.0f); mu[m] = mm; rs[m] = rsqrtf(fmaxf(s2 * (1.0f / 1024.0f) - mm * mm, 0.f) + LN_EPS_); }
;     __device__ __forceinline__ void operator()(const f32x4 (&acc)[2][2][4][2], const pg8::Unit& u, int wr, int wc, int fr, int fq) const {
;     ...
;         for (int ai = 0; ai < 2; ++ai) { float mu4[4], rs4[4]; row_stats4(stp, row0 + ai * 128, fq, mu4, rs4);
; #pragma unroll
;             for (int m = 0; m < 4; ++m) { const int row = row0 + ai * 128 + m * 16; const float mu = mu4[m], rs = rs4[m];
;                 f32x4 yv[2][2], gq[2][2], bq_[2][2];
; #pragma unroll
;                 for (int bj = 0; bj < 2; ++bj)
; #pragma unroll
;                     for (int n = 0; n < 2; ++n) { yv[bj][n] = *(const f32x4*)(Yin + (size_t)row * D_ + col0 + bj * 128 + 4 * n); gq[bj][n] = *(const f32x4*)(g + col0 + bj * 128 + 4 * n); bq_[bj][n] = *(const f32x4*)(b + col0 + bj * 128 + 4 * n); }
;                 asm volatile("" ::: "memory");
;                 float s1 = 0.f, s2 = 0.f;
; #pragma unroll
;                 for (int bj = 0; bj < 2; ++bj) { float* yp = Y + (size_t)row * D_ + col0 + bj * 128; f32x4 v[2];
; #pragma unroll
;                     for (int n = 0; n < 2; ++n) { v[n] = (((yv[bj][n] - mu) * rs) * gq[bj][n] + bq_[bj][n]) * ALPHA_ + acc[ai][bj][m][n] * sc;
;                         *(f32x4*)(yp + 4 * n) = v[n]; s1 += (v[n][0] + v[n][1]) + (v[n][2] + v[n][3]); s2 += (v[n][0] * v[n][0] + v[n][1] * v[n][1]) + (v[n][2] * v[n][2] + v[n][3] * v[n][3]); }
.LBB0_372:
	s_lshl_b32 s3, s3, 8
	s_add_i32 s3, s3, s53
	v_or_b32_e32 v158, s3, v182
	v_ashrrev_i32_e32 v159, 31, v158
	v_lshlrev_b64 v[130:131], 7, v[158:159]
	v_lshl_add_u64 v[136:137], v[146:147], 0, v[130:131]
	v_or_b32_e32 v180, 16, v158
	global_load_dwordx4 v[132:135], v[136:137], off
	global_load_dwordx4 v[166:169], v[136:137], off offset:16
	v_ashrrev_i32_e32 v181, 31, v180
	v_lshlrev_b64 v[172:173], 7, v[180:181]
	v_lshl_add_u64 v[136:137], v[146:147], 0, v[172:173]
	global_load_dwordx4 v[174:177], v[136:137], off
	global_load_dwordx4 v[186:189], v[136:137], off offset:16
	v_or_b32_e32 v170, 32, v158
	v_ashrrev_i32_e32 v171, 31, v170
	v_lshlrev_b64 v[164:165], 7, v[170:171]
	v_lshl_add_u64 v[136:137], v[146:147], 0, v[164:165]
	global_load_dwordx4 v[190:193], v[136:137], off
	global_load_dwordx4 v[196:199], v[136:137], off offset:16
	v_or_b32_e32 v162, 48, v158
	v_ashrrev_i32_e32 v163, 31, v162
	v_lshlrev_b64 v[160:161], 7, v[162:163]
	v_lshl_add_u64 v[204:205], v[146:147], 0, v[160:161]
	global_load_dwordx4 v[200:203], v[204:205], off
	s_nop 0
	global_load_dwordx4 v[204:207], v[204:205], off offset:16
	s_lshl_b32 s16, s2, 8
	s_lshl_b32 s17, s2, 3
	s_or_b32 s2, s16, s54
	v_or_b32_e32 v152, s2, v183
	v_ashrrev_i32_e32 v153, 31, v152
	v_lshlrev_b64 v[136:137], 12, v[158:159]
	v_lshlrev_b64 v[152:153], 2, v[152:153]
	v_lshl_add_u64 v[178:179], s[12:13], 0, v[136:137]
	v_lshl_add_u64 v[178:179], v[178:179], 0, v[152:153]
	v_lshl_add_u64 v[154:155], s[8:9], 0, v[152:153]
	v_lshl_add_u64 v[156:157], s[10:11], 0, v[152:153]
	global_load_dwordx4 v[208:211], v[178:179], off offset:16
	global_load_dwordx4 v[212:215], v[178:179], off
	global_load_dwordx4 v[216:219], v[154:155], off offset:16
	global_load_dwordx4 v[220:223], v[154:155], off
	global_load_dwordx4 v[234:237], v[156:157], off offset:16
	global_load_dwordx4 v[238:241], v[156:157], off
	s_mov_b32 s16, 0x3a800000
	s_mov_b32 s18, 0x3fd744fd
	s_load_dwordx16 s[60:75], s[34:35], 0x38
	s_or_b32 s24, s17, s57
	v_bitop3_b32 v194, s2, 56, v183 bitop3:0xc8
	s_ashr_i32 s40, s2, 6
	s_ashr_i32 s25, s24, 31
	s_waitcnt lgkmcnt(0)
	v_lshl_add_u64 v[136:137], s[74:75], 0, v[136:137]
	v_lshl_add_u64 v[136:137], v[136:137], 0, v[152:153]
	s_ashr_i32 s41, s40, 31
	s_waitcnt vmcnt(0)
	v_mov_b32_e32 v224, v132
	v_mov_b32_e32 v225, v166
	v_mov_b32_e32 v228, v134
	v_mov_b32_e32 v229, v168
	v_mov_b32_e32 v166, v133
	v_mov_b32_e32 v168, v135
	v_pk_add_f32 v[132:133], v[224:225], v[228:229]
	v_pk_add_f32 v[134:135], v[166:167], v[168:169]
	v_pk_add_f32 v[132:133], v[132:133], v[132:133] op_sel:[0,1] op_sel_hi:[1,0]
	v_pk_add_f32 v[134:135], v[134:135], v[134:135] op_sel:[0,1] op_sel_hi:[1,0]
	v_mov_b32_e32 v166, v174
	v_mov_b32_e32 v167, v186
	v_mov_b32_e32 v168, v176
	v_mov_b32_e32 v169, v188
	v_mov_b32_e32 v0, v132
	v_mov_b32_e32 v133, v134
	v_pk_add_f32 v[166:167], v[166:167], v[168:169]
	v_permlane16_swap_b32_e32 v132, v0
	v_permlane16_swap_b32_e32 v134, v133
	v_mov_b32_e32 v186, v175
	v_mov_b32_e32 v188, v177
	v_pk_add_f32 v[166:167], v[166:167], v[166:167] op_sel:[0,1] op_sel_hi:[1,0]
	v_add_f32_e32 v177, v132, v0
	v_add_f32_e32 v176, v134, v133
	v_pk_add_f32 v[168:169], v[186:187], v[188:189]
	v_mov_b32_e32 v135, v166
	v_mov_b32_e32 v187, v177
	v_mov_b32_e32 v186, v176
	v_permlane16_swap_b32_e32 v166, v135
	v_permlane32_swap_b32_e32 v177, v187
	v_permlane32_swap_b32_e32 v176, v186
	v_add_f32_e32 v133, v166, v135
	v_pk_add_f32 v[166:167], v[176:177], v[186:187]
	v_pk_add_f32 v[168:169], v[168:169], v[168:169] op_sel:[0,1] op_sel_hi:[1,0]
	v_pk_mul_f32 v[224:225], v[166:167], s[16:17] op_sel_hi:[1,0]
	v_mov_b32_e32 v159, v168
	v_fma_f32 v0, -v225, v225, v224
	v_max_f32_e32 v0, 0, v0
	v_permlane16_swap_b32_e32 v168, v159
	v_add_f32_e32 v0, 0x3727c5ac, v0
	s_mov_b32 s16, 0x800000
	v_add_f32_e32 v132, v168, v159
	v_mul_f32_e32 v159, 0x4b800000, v0
	v_cmp_gt_f32_e32 vcc, s16, v0
	v_mov_b32_e32 v174, v190
	v_mov_b32_e32 v175, v196
	v_cndmask_b32_e32 v0, v0, v159, vcc
	v_rsq_f32_e32 v0, v0
	v_mov_b32_e32 v166, v192
	v_mov_b32_e32 v167, v198
	v_pk_add_f32 v[166:167], v[174:175], v[166:167]
	v_mul_f32_e32 v159, 0x45800000, v0
	v_pk_add_f32 v[166:167], v[166:167], v[166:167] op_sel:[0,1] op_sel_hi:[1,0]
	v_mov_b32_e32 v196, v191
	v_mov_b32_e32 v198, v193
	v_cndmask_b32_e32 v0, v0, v159, vcc
	v_pk_add_f32 v[168:169], v[196:197], v[198:199]
	v_mov_b32_e32 v159, v166
	v_pk_add_f32 v[168:169], v[168:169], v[168:169] op_sel:[0,1] op_sel_hi:[1,0]
	s_nop 0
	v_permlane16_swap_b32_e32 v166, v159
	v_add_f32_e32 v175, v166, v159
	v_mov_b32_e32 v159, v168
	s_nop 1
	v_permlane16_swap_b32_e32 v168, v159
	global_load_dwordx4 v[186:189], v[178:179], off offset:528
	global_load_dwordx4 v[190:193], v[178:179], off offset:512
	v_add_f32_e32 v174, v168, v159
	v_mov_b32_e32 v166, v200
	v_mov_b32_e32 v167, v204
	v_mov_b32_e32 v168, v202
	v_mov_b32_e32 v169, v206
	v_mov_b32_e32 v204, v201
	v_mov_b32_e32 v206, v203
	v_pk_add_f32 v[166:167], v[166:167], v[168:169]
	v_pk_add_f32 v[168:169], v[204:205], v[206:207]
	global_load_dwordx4 v[196:199], v[154:155], off offset:528
	global_load_dwordx4 v[200:203], v[154:155], off offset:512
	global_load_dwordx4 v[204:207], v[156:157], off offset:528
	global_load_dwordx4 v[242:245], v[156:157], off offset:512
	v_sub_f32_e32 v179, v215, v225
	v_sub_f32_e32 v178, v214, v225
	v_sub_f32_e32 v213, v213, v225
	v_sub_f32_e32 v212, v212, v225
	v_pk_mul_f32 v[212:213], v[0:1], v[212:213] op_sel_hi:[0,1]
	v_pk_mul_f32 v[178:179], v[0:1], v[178:179] op_sel_hi:[0,1]
	v_pk_fma_f32 v[178:179], v[222:223], v[178:179], v[240:241]
	v_pk_fma_f32 v[212:213], v[220:221], v[212:213], v[238:239]
; __device__ __forceinline__ float xsum16(float v) { const auto r = __builtin_amdgcn_permlane16_swap(__float_as_uint(v), __float_as_uint(v), false, false); return __uint_as_float(r[0]) + __uint_as_float(r[1]); }
; __device__ __forceinline__ float xsum32(float v) { const auto r = __builtin_amdgcn_permlane32_swap(__float_as_uint(v), __float_as_uint(v), false, false); return __uint_as_float(r[0]) + __uint_as_float(r[1]); }
; __device__ __forceinline__ size_t blk_off(int r, int c, int K) { return (size_t)(r >> 8) * 256 * K + (size_t)(c >> 6) * (256 * 64) + (size_t)((r & 255) * 64 + (c & 63)); }
; __device__ __forceinline__ u32x4 pack8(const f32x4 a, const f32x4 b) { u32x4 w; w.x = cvt_pk_bf16(a[0], a[1]); w.y = cvt_pk_bf16(a[2], a[3]); w.z = cvt_pk_bf16(b[0], b[1]); w.w = cvt_pk_bf16(b[2], b[3]); return w; }
;     __device__ __forceinline__ void operator()(const f32x4 (&acc)[2][2][4][2], const pg8::Unit& u, int wr, int wc, int fr, int fq) const {
;     ...
;             for (int m = 0; m < 4; ++m) { const int row = row0 + ai * 128 + m * 16; const float mu = mu4[m], rs = rs4[m];
;                 f32x4 yv[2][2], gq[2][2], bq_[2][2];
; #pragma unroll
;                 for (int bj = 0; bj < 2; ++bj)
; #pragma unroll
;                     for (int n = 0; n < 2; ++n) { yv[bj][n] = *(const f32x4*)(Yin + (size_t)row * D_ + col0 + bj * 128 + 4 * n); gq[bj][n] = *(const f32x4*)(g + col0 + bj * 128 + 4 * n); bq_[bj][n] = *(const f32x4*)(b + col0 + bj * 128 + 4 * n); }
;                 asm volatile("" ::: "memory");
;                 float s1 = 0.f, s2 = 0.f;
; #pragma unroll
;                 for (int bj = 0; bj < 2; ++bj) { float* yp = Y + (size_t)row * D_ + col0 + bj * 128; f32x4 v[2];
; #pragma unroll
;                     for (int n = 0; n < 2; ++n) { v[n] = (((yv[bj][n] - mu) * rs) * gq[bj][n] + bq_[bj][n]) * ALPHA_ + acc[ai][bj][m][n] * sc;
;                         *(f32x4*)(yp + 4 * n) = v[n]; s1 += (v[n][0] + v[n][1]) + (v[n][2] + v[n][3]); s2 += (v[n][0] * v[n][0] + v[n][1] * v[n][1]) + (v[n][2] * v[n][2] + v[n][3] * v[n][3]); }
;                     *(u32x4*)(Yb + blk_off(row, col0 + bj * 128, D_)) = pack8(v[0], v[1]); }
;                 s1 = xsum32(xsum16(s1)); s2 = xsum32(xsum16(s2));
;                 if (fq == 0) *(f32x2*)(stn + (size_t)row * 32 + (u.pn * 4 + wc) * 2) = (f32x2){s1, s2}; asm volatile("" ::: "memory"); } }
	v_pk_mul_f32 v[178:179], v[178:179], s[18:19] op_sel_hi:[1,0]
	v_pk_mul_f32 v[212:213], v[212:213], s[18:19] op_sel_hi:[1,0]
	v_pk_fma_f32 v[128:129], v[128:129], 0.5, v[178:179] op_sel_hi:[1,0,1]
	v_pk_fma_f32 v[126:127], v[126:127], 0.5, v[212:213] op_sel_hi:[1,0,1]
	v_add_f32_e32 v179, v128, v129
	v_add_f32_e32 v178, v126, v127
	v_add_f32_e32 v178, v178, v179
	v_add_f32_e32 v195, 0, v178
	v_mul_f32_e32 v178, v127, v127
	v_mul_f32_e32 v179, v129, v129
	v_fmac_f32_e32 v178, v126, v126
	v_fmac_f32_e32 v179, v128, v128
	v_add_f32_e32 v212, v178, v179
	v_sub_f32_e32 v179, v211, v225
	v_sub_f32_e32 v178, v210, v225
	v_sub_f32_e32 v209, v209, v225
	v_sub_f32_e32 v208, v208, v225
	v_pk_mul_f32 v[208:209], v[0:1], v[208:209] op_sel_hi:[0,1]
	v_pk_mul_f32 v[178:179], v[0:1], v[178:179] op_sel_hi:[0,1]
	v_pk_fma_f32 v[178:179], v[218:219], v[178:179], v[236:237]
	v_pk_fma_f32 v[208:209], v[216:217], v[208:209], v[234:235]
	v_pk_mul_f32 v[178:179], v[178:179], s[18:19] op_sel_hi:[1,0]
	v_pk_mul_f32 v[208:209], v[208:209], s[18:19] op_sel_hi:[1,0]
	v_pk_add_f32 v[166:167], v[166:167], v[166:167] op_sel:[0,1] op_sel_hi:[1,0]
	v_pk_fma_f32 v[124:125], v[124:125], 0.5, v[178:179] op_sel_hi:[1,0,1]
	v_pk_fma_f32 v[122:123], v[122:123], 0.5, v[208:209] op_sel_hi:[1,0,1]
	v_mov_b32_e32 v159, v166
	v_add_f32_e32 v178, v122, v123
	v_add_f32_e32 v179, v124, v125
	v_pk_add_f32 v[168:169], v[168:169], v[168:169] op_sel:[0,1] op_sel_hi:[1,0]
	v_permlane16_swap_b32_e32 v166, v159
	v_add_f32_e32 v178, v178, v179
	v_add_f32_e32 v167, v166, v159
	v_mov_b32_e32 v159, v168
	v_add_f32_e32 v178, v195, v178
	v_mul_f32_e32 v179, v123, v123
	v_mul_f32_e32 v195, v125, v125
	v_permlane16_swap_b32_e32 v168, v159
	s_ashr_i32 s16, s3, 8
	s_nop 0
	s_nop 1
	v_bfe_u32 v135, v227, 4, 1
	v_sub_u32_e32 v135, 0, v135
	v_lshlrev_b32_e32 v134, 4, v135
	v_lshl_add_u64 v[134:135], v[136:137], 0, v[134:135]
	v_permlane16_swap_b32_e32 v126, v122
	v_permlane16_swap_b32_e32 v127, v123
	v_permlane16_swap_b32_e32 v128, v124
	v_permlane16_swap_b32_e32 v129, v125
	global_store_dwordx4 v[134:135], v[126:129], off
	global_store_dwordx4 v[134:135], v[122:125], off offset:32
	s_nop 1
	v_permlane16_swap_b32_e32 v126, v122
	v_permlane16_swap_b32_e32 v127, v123
	v_permlane16_swap_b32_e32 v128, v124
	v_permlane16_swap_b32_e32 v129, v125
	v_fmac_f32_e32 v179, v122, v122
	v_fmac_f32_e32 v195, v124, v124
	v_cvt_pk_bf16_f32 v126, v126, v127
	v_cvt_pk_bf16_f32 v127, v128, v129
	v_cvt_pk_bf16_f32 v128, v122, v123
	v_cvt_pk_bf16_f32 v129, v124, v125
	v_add_f32_e32 v166, v168, v159
	s_ashr_i32 s17, s16, 31
	v_lshlrev_b32_e32 v159, 6, v158
	s_movk_i32 s3, 0x33c0
	s_lshl_b64 s[16:17], s[16:17], 19
	v_and_or_b32 v159, v159, s3, v194
	v_readlane_b32 s2, v253, 59
	v_readlane_b32 s3, v253, 60
	s_add_u32 s16, s2, s16
	s_addc_u32 s17, s3, s17
	s_lshl_b64 s[28:29], s[40:41], 15
	s_waitcnt vmcnt(6)
	v_sub_f32_e32 v123, v193, v225
	v_sub_f32_e32 v122, v192, v225
	v_sub_f32_e32 v125, v191, v225
	v_sub_f32_e32 v124, v190, v225
	v_pk_mul_f32 v[124:125], v[0:1], v[124:125] op_sel_hi:[0,1]
	v_pk_mul_f32 v[122:123], v[0:1], v[122:123] op_sel_hi:[0,1]
	s_add_u32 s50, s16, s28
	s_addc_u32 s51, s17, s29
	v_lshlrev_b32_e32 v159, 1, v159
	global_store_dwordx4 v159, v[126:129], s[50:51]
	s_waitcnt vmcnt(3)
	v_pk_fma_f32 v[122:123], v[202:203], v[122:123], v[244:245]
	v_pk_fma_f32 v[124:125], v[200:201], v[124:125], v[242:243]
	v_pk_mul_f32 v[122:123], v[122:123], s[18:19] op_sel_hi:[1,0]
	v_pk_mul_f32 v[124:125], v[124:125], s[18:19] op_sel_hi:[1,0]
	v_pk_fma_f32 v[120:121], v[120:121], 0.5, v[122:123] op_sel_hi:[1,0,1]
	v_pk_fma_f32 v[118:119], v[118:119], 0.5, v[124:125] op_sel_hi:[1,0,1]
	v_add_f32_e32 v123, v120, v121
	v_add_f32_e32 v122, v118, v119
	v_add_f32_e32 v122, v122, v123
	v_add_f32_e32 v126, v178, v122
	v_mul_f32_e32 v122, v119, v119
	v_mul_f32_e32 v123, v121, v121
	v_add_f32_e32 v179, v179, v195
	v_fmac_f32_e32 v122, v118, v118
	v_fmac_f32_e32 v123, v120, v120
	v_add_f32_e32 v179, v212, v179
	v_add_f32_e32 v122, v122, v123
	v_add_f32_e32 v127, v179, v122
	v_sub_f32_e32 v123, v189, v225
	v_sub_f32_e32 v122, v188, v225
	v_sub_f32_e32 v125, v187, v225
	v_sub_f32_e32 v124, v186, v225
	v_pk_mul_f32 v[124:125], v[0:1], v[124:125] op_sel_hi:[0,1]
	v_pk_mul_f32 v[122:123], v[0:1], v[122:123] op_sel_hi:[0,1]
	v_pk_fma_f32 v[122:123], v[198:199], v[122:123], v[206:207]
	v_pk_fma_f32 v[124:125], v[196:197], v[124:125], v[204:205]
	v_pk_mul_f32 v[122:123], v[122:123], s[18:19] op_sel_hi:[1,0]
	v_pk_mul_f32 v[124:125], v[124:125], s[18:19] op_sel_hi:[1,0]
	v_pk_fma_f32 v[116:117], v[116:117], 0.5, v[122:123] op_sel_hi:[1,0,1]
	v_pk_fma_f32 v[114:115], v[114:115], 0.5, v[124:125] op_sel_hi:[1,0,1]
	v_add_f32_e32 v122, v116, v117
	v_add_f32_e32 v0, v114, v115
	v_add_f32_e32 v0, v0, v122
	v_mul_f32_e32 v122, v115, v115
	v_mul_f32_e32 v123, v117, v117
	v_add_f32_e32 v0, v126, v0
	v_fmac_f32_e32 v122, v114, v114
	v_fmac_f32_e32 v123, v116, v116
	s_nop 0
	s_nop 1
	v_bfe_u32 v125, v227, 4, 1
	v_sub_u32_e32 v125, 0, v125
	v_lshlrev_b32_e32 v124, 4, v125
	v_lshl_add_u64 v[124:125], v[136:137], 0, v[124:125]
	v_permlane16_swap_b32_e32 v118, v114
	v_permlane16_swap_b32_e32 v119, v115
	v_permlane16_swap_b32_e32 v120, v116
	v_permlane16_swap_b32_e32 v121, v117
	global_store_dwordx4 v[124:125], v[118:121], off offset:512
	global_store_dwordx4 v[124:125], v[114:117], off offset:544
	s_nop 1
	v_permlane16_swap_b32_e32 v118, v114
	v_permlane16_swap_b32_e32 v119, v115
	v_permlane16_swap_b32_e32 v120, v116
	v_permlane16_swap_b32_e32 v121, v117
	v_add_f32_e32 v122, v122, v123
	v_cvt_pk_bf16_f32 v118, v118, v119
	v_cvt_pk_bf16_f32 v119, v120, v121
	v_cvt_pk_bf16_f32 v120, v114, v115
	v_mov_b32_e32 v114, v0
	v_add_f32_e32 v122, v127, v122
	s_nop 0
	v_permlane16_swap_b32_e32 v0, v114
	s_or_b32 s2, s40, 2
	v_add_f32_e32 v114, v0, v114
	v_mov_b32_e32 v0, v122
	s_ashr_i32 s3, s2, 31
	s_nop 0
	v_permlane16_swap_b32_e32 v122, v0
	s_lshl_b64 s[40:41], s[2:3], 15
	v_add_f32_e32 v115, v122, v0
	v_mov_b32_e32 v135, v133
	v_mov_b32_e32 v134, v132
	v_mov_b32_e32 v177, v175
	v_mov_b32_e32 v176, v174
	v_mov_b32_e32 v169, v167
	v_mov_b32_e32 v168, v166
	v_cvt_pk_bf16_f32 v121, v116, v117
	s_add_u32 s42, s16, s40
	v_mov_b32_e32 v116, v114
	v_mov_b32_e32 v117, v115
	v_permlane32_swap_b32_e32 v133, v135
	v_permlane32_swap_b32_e32 v132, v134
	v_permlane32_swap_b32_e32 v175, v177
	v_permlane32_swap_b32_e32 v174, v176
	v_permlane32_swap_b32_e32 v167, v169
	v_permlane32_swap_b32_e32 v166, v168
	s_addc_u32 s43, s17, s41
	v_permlane32_swap_b32_e32 v114, v116
	v_permlane32_swap_b32_e32 v115, v117
	global_store_dwordx4 v159, v[118:121], s[42:43]
	s_and_saveexec_b64 s[26:27], s[44:45]
	s_cbranch_execz .LBB0_374
	v_pk_add_f32 v[114:115], v[114:115], v[116:117]
	v_lshl_add_u64 v[116:117], s[30:31], 0, v[130:131]
	v_lshl_add_u64 v[116:117], s[24:25], 2, v[116:117]
	global_store_dwordx2 v[116:117], v[114:115], off
; __device__ __forceinline__ float xsum16(float v) { const auto r = __builtin_amdgcn_permlane16_swap(__float_as_uint(v), __float_as_uint(v), false, false); return __uint_as_float(r[0]) + __uint_as_float(r[1]); }
; __device__ __forceinline__ float xsum32(float v) { const auto r = __builtin_amdgcn_permlane32_swap(__float_as_uint(v), __float_as_uint(v), false, false); return __uint_as_float(r[0]) + __uint_as_float(r[1]); }
; __device__ __forceinline__ size_t blk_off(int r, int c, int K) { return (size_t)(r >> 8) * 256 * K + (size_t)(c >> 6) * (256 * 64) + (size_t)((r & 255) * 64 + (c & 63)); }
; __device__ __forceinline__ u32x4 pack8(const f32x4 a, const f32x4 b) { u32x4 w; w.x = cvt_pk_bf16(a[0], a[1]); w.y = cvt_pk_bf16(a[2], a[3]); w.z = cvt_pk_bf16(b[0], b[1]); w.w = cvt_pk_bf16(b[2], b[3]); return w; }
;     __device__ __forceinline__ void operator()(const f32x4 (&acc)[2][2][4][2], const pg8::Unit& u, int wr, int wc, int fr, int fq) const {
;     ...
;             for (int m = 0; m < 4; ++m) { const int row = row0 + ai * 128 + m * 16; const float mu = mu4[m], rs = rs4[m];
;                 f32x4 yv[2][2], gq[2][2], bq_[2][2];
; #pragma unroll
;                 for (int bj = 0; bj < 2; ++bj)
; #pragma unroll
;                     for (int n = 0; n < 2; ++n) { yv[bj][n] = *(const f32x4*)(Yin + (size_t)row * D_ + col0 + bj * 128 + 4 * n); gq[bj][n] = *(const f32x4*)(g + col0 + bj * 128 + 4 * n); bq_[bj][n] = *(const f32x4*)(b + col0 + bj * 128 + 4 * n); }
;                 asm volatile("" ::: "memory");
;                 float s1 = 0.f, s2 = 0.f;
; #pragma unroll
;                 for (int bj = 0; bj < 2; ++bj) { float* yp = Y + (size_t)row * D_ + col0 + bj * 128; f32x4 v[2];
; #pragma unroll
;                     for (int n = 0; n < 2; ++n) { v[n] = (((yv[bj][n] - mu) * rs) * gq[bj][n] + bq_[bj][n]) * ALPHA_ + acc[ai][bj][m][n] * sc;
;                         *(f32x4*)(yp + 4 * n) = v[n]; s1 += (v[n][0] + v[n][1]) + (v[n][2] + v[n][3]); s2 += (v[n][0] * v[n][0] + v[n][1] * v[n][1]) + (v[n][2] * v[n][2] + v[n][3] * v[n][3]); }
;                     *(u32x4*)(Yb + blk_off(row, col0 + bj * 128, D_)) = pack8(v[0], v[1]); }
;                 s1 = xsum32(xsum16(s1)); s2 = xsum32(xsum16(s2));
;                 if (fq == 0) *(f32x2*)(stn + (size_t)row * 32 + (u.pn * 4 + wc) * 2) = (f32x2){s1, s2}; asm volatile("" ::: "memory"); } }
.LBB0_374:
	s_or_b64 exec, exec, s[26:27]
	v_pk_add_f32 v[114:115], v[132:133], v[134:135]
	s_mov_b32 s2, 0x3a800000
	v_pk_mul_f32 v[178:179], v[114:115], s[2:3] op_sel_hi:[1,0]
	s_mov_b32 s2, 0x800000
	v_fma_f32 v0, -v179, v179, v178
	v_max_f32_e32 v0, 0, v0
	v_add_f32_e32 v0, 0x3727c5ac, v0
	v_cmp_gt_f32_e32 vcc, s2, v0
	v_mul_f32_e32 v114, 0x4b800000, v0
	v_lshlrev_b64 v[212:213], 12, v[180:181]
	v_cndmask_b32_e32 v0, v0, v114, vcc
	v_rsq_f32_e32 v0, v0
	v_lshlrev_b32_e32 v159, 6, v180
	s_movk_i32 s2, 0x37c0
	v_mul_f32_e32 v114, 0x45800000, v0
	v_cndmask_b32_e32 v0, v0, v114, vcc
	v_lshl_add_u64 v[114:115], s[12:13], 0, v[212:213]
	v_lshl_add_u64 v[118:119], v[114:115], 0, v[152:153]
	global_load_dwordx4 v[186:189], v[118:119], off offset:16
	global_load_dwordx4 v[190:193], v[118:119], off
	global_load_dwordx4 v[196:199], v[154:155], off offset:16
	global_load_dwordx4 v[200:203], v[154:155], off
	global_load_dwordx4 v[204:207], v[156:157], off offset:16
	global_load_dwordx4 v[208:211], v[156:157], off
	global_load_dwordx4 v[114:117], v[118:119], off offset:528
	global_load_dwordx4 v[134:137], v[118:119], off offset:512
	s_nop 0
	global_load_dwordx4 v[118:121], v[154:155], off offset:528
	global_load_dwordx4 v[126:129], v[154:155], off offset:512
	global_load_dwordx4 v[122:125], v[156:157], off offset:528
	global_load_dwordx4 v[130:133], v[156:157], off offset:512
	v_and_or_b32 v159, v159, s2, v194
	s_load_dwordx16 s[60:75], s[34:35], 0x38
	s_mov_b32 s2, 0x3fd744fd
	v_lshlrev_b32_e32 v159, 1, v159
	s_waitcnt lgkmcnt(0)
	v_lshl_add_u64 v[180:181], s[74:75], 0, v[212:213]
	v_lshl_add_u64 v[180:181], v[180:181], 0, v[152:153]
	s_waitcnt vmcnt(11)
	v_sub_f32_e32 v189, v189, v179
	s_waitcnt vmcnt(10)
	v_sub_f32_e32 v193, v193, v179
	v_sub_f32_e32 v192, v192, v179
	v_sub_f32_e32 v191, v191, v179
	v_sub_f32_e32 v190, v190, v179
	v_pk_mul_f32 v[190:191], v[0:1], v[190:191] op_sel_hi:[0,1]
	v_pk_mul_f32 v[192:193], v[0:1], v[192:193] op_sel_hi:[0,1]
	v_sub_f32_e32 v188, v188, v179
	v_sub_f32_e32 v187, v187, v179
	v_sub_f32_e32 v186, v186, v179
	s_waitcnt vmcnt(6)
	v_pk_fma_f32 v[192:193], v[202:203], v[192:193], v[210:211]
	v_pk_fma_f32 v[190:191], v[200:201], v[190:191], v[208:209]
	v_pk_mul_f32 v[186:187], v[0:1], v[186:187] op_sel_hi:[0,1]
	v_pk_mul_f32 v[188:189], v[0:1], v[188:189] op_sel_hi:[0,1]
	v_pk_mul_f32 v[190:191], v[190:191], s[2:3] op_sel_hi:[1,0]
	v_pk_mul_f32 v[192:193], v[192:193], s[2:3] op_sel_hi:[1,0]
	v_pk_fma_f32 v[188:189], v[198:199], v[188:189], v[206:207]
	v_pk_fma_f32 v[186:187], v[196:197], v[186:187], v[204:205]
	v_pk_fma_f32 v[112:113], v[112:113], 0.5, v[192:193] op_sel_hi:[1,0,1]
	v_pk_fma_f32 v[110:111], v[110:111], 0.5, v[190:191] op_sel_hi:[1,0,1]
	v_pk_mul_f32 v[186:187], v[186:187], s[2:3] op_sel_hi:[1,0]
	v_pk_mul_f32 v[188:189], v[188:189], s[2:3] op_sel_hi:[1,0]
	v_add_f32_e32 v178, v110, v111
	v_add_f32_e32 v190, v112, v113
	v_pk_fma_f32 v[108:109], v[108:109], 0.5, v[188:189] op_sel_hi:[1,0,1]
	v_pk_fma_f32 v[106:107], v[106:107], 0.5, v[186:187] op_sel_hi:[1,0,1]
	v_add_f32_e32 v178, v178, v190
	v_add_f32_e32 v186, v106, v107
	v_add_f32_e32 v187, v108, v109
	v_add_f32_e32 v178, 0, v178
	v_add_f32_e32 v186, v186, v187
	v_mul_f32_e32 v190, v111, v111
	v_mul_f32_e32 v191, v113, v113
	v_add_f32_e32 v178, v178, v186
	v_mul_f32_e32 v186, v107, v107
	v_mul_f32_e32 v187, v109, v109
	s_nop 0
	v_fmac_f32_e32 v190, v110, v110
	v_fmac_f32_e32 v191, v112, v112
	s_nop 1
	v_bfe_u32 v189, v227, 4, 1
	v_sub_u32_e32 v189, 0, v189
	v_lshlrev_b32_e32 v188, 4, v189
	v_lshl_add_u64 v[188:189], v[180:181], 0, v[188:189]
	v_permlane16_swap_b32_e32 v110, v106
	v_permlane16_swap_b32_e32 v111, v107
	v_permlane16_swap_b32_e32 v112, v108
	v_permlane16_swap_b32_e32 v113, v109
	global_store_dwordx4 v[188:189], v[110:113], off
	global_store_dwordx4 v[188:189], v[106:109], off offset:32
	s_nop 1
	v_permlane16_swap_b32_e32 v110, v106
	v_permlane16_swap_b32_e32 v111, v107
	v_permlane16_swap_b32_e32 v112, v108
	v_permlane16_swap_b32_e32 v113, v109
	v_fmac_f32_e32 v186, v106, v106
	v_fmac_f32_e32 v187, v108, v108
	v_cvt_pk_bf16_f32 v110, v110, v111
	v_cvt_pk_bf16_f32 v111, v112, v113
	v_cvt_pk_bf16_f32 v112, v106, v107
	v_cvt_pk_bf16_f32 v113, v108, v109
	s_waitcnt vmcnt(6)
	v_sub_f32_e32 v107, v137, v179
	v_sub_f32_e32 v106, v136, v179
	v_sub_f32_e32 v109, v135, v179
	v_sub_f32_e32 v108, v134, v179
	v_pk_mul_f32 v[108:109], v[0:1], v[108:109] op_sel_hi:[0,1]
	v_pk_mul_f32 v[106:107], v[0:1], v[106:107] op_sel_hi:[0,1]
	s_waitcnt vmcnt(2)
; __device__ __forceinline__ float xsum16(float v) { const auto r = __builtin_amdgcn_permlane16_swap(__float_as_uint(v), __float_as_uint(v), false, false); return __uint_as_float(r[0]) + __uint_as_float(r[1]); }
; __device__ __forceinline__ float xsum32(float v) { const auto r = __builtin_amdgcn_permlane32_swap(__float_as_uint(v), __float_as_uint(v), false, false); return __uint_as_float(r[0]) + __uint_as_float(r[1]); }
; __device__ __forceinline__ size_t blk_off(int r, int c, int K) { return (size_t)(r >> 8) * 256 * K + (size_t)(c >> 6) * (256 * 64) + (size_t)((r & 255) * 64 + (c & 63)); }
; __device__ __forceinline__ u32x4 pack8(const f32x4 a, const f32x4 b) { u32x4 w; w.x = cvt_pk_bf16(a[0], a[1]); w.y = cvt_pk_bf16(a[2], a[3]); w.z = cvt_pk_bf16(b[0], b[1]); w.w = cvt_pk_bf16(b[2], b[3]); return w; }
;     __device__ __forceinline__ void operator()(const f32x4 (&acc)[2][2][4][2], const pg8::Unit& u, int wr, int wc, int fr, int fq) const {
;     ...
;             for (int m = 0; m < 4; ++m) { const int row = row0 + ai * 128 + m * 16; const float mu = mu4[m], rs = rs4[m];
;                 f32x4 yv[2][2], gq[2][2], bq_[2][2];
; #pragma unroll
;                 for (int bj = 0; bj < 2; ++bj)
; #pragma unroll
;                     for (int n = 0; n < 2; ++n) { yv[bj][n] = *(const f32x4*)(Yin + (size_t)row * D_ + col0 + bj * 128 + 4 * n); gq[bj][n] = *(const f32x4*)(g + col0 + bj * 128 + 4 * n); bq_[bj][n] = *(const f32x4*)(b + col0 + bj * 128 + 4 * n); }
;                 asm volatile("" ::: "memory");
;                 float s1 = 0.f, s2 = 0.f;
; #pragma unroll
;                 for (int bj = 0; bj < 2; ++bj) { float* yp = Y + (size_t)row * D_ + col0 + bj * 128; f32x4 v[2];
; #pragma unroll
;                     for (int n = 0; n < 2; ++n) { v[n] = (((yv[bj][n] - mu) * rs) * gq[bj][n] + bq_[bj][n]) * ALPHA_ + acc[ai][bj][m][n] * sc;
;                         *(f32x4*)(yp + 4 * n) = v[n]; s1 += (v[n][0] + v[n][1]) + (v[n][2] + v[n][3]); s2 += (v[n][0] * v[n][0] + v[n][1] * v[n][1]) + (v[n][2] * v[n][2] + v[n][3] * v[n][3]); }
;                     *(u32x4*)(Yb + blk_off(row, col0 + bj * 128, D_)) = pack8(v[0], v[1]); }
;                 s1 = xsum32(xsum16(s1)); s2 = xsum32(xsum16(s2));
;                 if (fq == 0) *(f32x2*)(stn + (size_t)row * 32 + (u.pn * 4 + wc) * 2) = (f32x2){s1, s2}; asm volatile("" ::: "memory"); } }
	v_pk_fma_f32 v[106:107], v[128:129], v[106:107], v[132:133]
	v_pk_fma_f32 v[108:109], v[126:127], v[108:109], v[130:131]
	v_pk_mul_f32 v[106:107], v[106:107], s[2:3] op_sel_hi:[1,0]
	v_pk_mul_f32 v[108:109], v[108:109], s[2:3] op_sel_hi:[1,0]
	v_pk_fma_f32 v[104:105], v[104:105], 0.5, v[106:107] op_sel_hi:[1,0,1]
	v_pk_fma_f32 v[102:103], v[102:103], 0.5, v[108:109] op_sel_hi:[1,0,1]
	v_add_f32_e32 v107, v104, v105
	v_add_f32_e32 v106, v102, v103
	v_add_f32_e32 v106, v106, v107
	global_store_dwordx4 v159, v[110:113], s[50:51]
	v_mul_f32_e32 v107, v105, v105
	v_add_f32_e32 v190, v190, v191
	v_add_f32_e32 v110, v178, v106
	v_mul_f32_e32 v106, v103, v103
	v_add_f32_e32 v186, v186, v187
	v_fmac_f32_e32 v106, v102, v102
	v_fmac_f32_e32 v107, v104, v104
	v_add_f32_e32 v186, v190, v186
	v_add_f32_e32 v106, v106, v107
	v_add_f32_e32 v111, v186, v106
	v_sub_f32_e32 v107, v117, v179
	v_sub_f32_e32 v106, v116, v179
	v_sub_f32_e32 v109, v115, v179
	v_sub_f32_e32 v108, v114, v179
	v_pk_mul_f32 v[108:109], v[0:1], v[108:109] op_sel_hi:[0,1]
	v_pk_mul_f32 v[106:107], v[0:1], v[106:107] op_sel_hi:[0,1]
	v_pk_fma_f32 v[106:107], v[120:121], v[106:107], v[124:125]
	v_pk_fma_f32 v[108:109], v[118:119], v[108:109], v[122:123]
	v_pk_mul_f32 v[106:107], v[106:107], s[2:3] op_sel_hi:[1,0]
	v_pk_mul_f32 v[108:109], v[108:109], s[2:3] op_sel_hi:[1,0]
	v_pk_fma_f32 v[100:101], v[100:101], 0.5, v[106:107] op_sel_hi:[1,0,1]
	v_pk_fma_f32 v[98:99], v[98:99], 0.5, v[108:109] op_sel_hi:[1,0,1]
	v_add_f32_e32 v106, v100, v101
	v_add_f32_e32 v0, v98, v99
	v_add_f32_e32 v0, v0, v106
	v_mul_f32_e32 v106, v99, v99
	v_mul_f32_e32 v107, v101, v101
	v_add_f32_e32 v0, v110, v0
	v_fmac_f32_e32 v106, v98, v98
	v_fmac_f32_e32 v107, v100, v100
	s_nop 0
	s_nop 1
	v_bfe_u32 v109, v227, 4, 1
	v_sub_u32_e32 v109, 0, v109
	v_lshlrev_b32_e32 v108, 4, v109
	v_lshl_add_u64 v[108:109], v[180:181], 0, v[108:109]
	v_permlane16_swap_b32_e32 v102, v98
	v_permlane16_swap_b32_e32 v103, v99
	v_permlane16_swap_b32_e32 v104, v100
	v_permlane16_swap_b32_e32 v105, v101
	global_store_dwordx4 v[108:109], v[102:105], off offset:512
	global_store_dwordx4 v[108:109], v[98:101], off offset:544
	s_nop 1
	v_permlane16_swap_b32_e32 v102, v98
	v_permlane16_swap_b32_e32 v103, v99
	v_permlane16_swap_b32_e32 v104, v100
	v_permlane16_swap_b32_e32 v105, v101
	v_add_f32_e32 v106, v106, v107
	v_cvt_pk_bf16_f32 v102, v102, v103
	v_cvt_pk_bf16_f32 v103, v104, v105
	v_cvt_pk_bf16_f32 v104, v98, v99
	v_mov_b32_e32 v98, v0
	v_add_f32_e32 v106, v111, v106
	s_nop 0
	v_permlane16_swap_b32_e32 v0, v98
	v_add_f32_e32 v98, v0, v98
	v_mov_b32_e32 v0, v106
	s_nop 1
	v_permlane16_swap_b32_e32 v106, v0
	v_add_f32_e32 v99, v106, v0
	v_cvt_pk_bf16_f32 v105, v100, v101
	v_mov_b32_e32 v100, v98
	v_mov_b32_e32 v101, v99
	s_nop 0
	v_permlane32_swap_b32_e32 v98, v100
	v_permlane32_swap_b32_e32 v99, v101
	global_store_dwordx4 v159, v[102:105], s[42:43]
	s_and_saveexec_b64 s[26:27], s[44:45]
	s_cbranch_execz .LBB0_376
	v_pk_add_f32 v[98:99], v[98:99], v[100:101]
	v_lshl_add_u64 v[100:101], s[30:31], 0, v[172:173]
	v_lshl_add_u64 v[100:101], s[24:25], 2, v[100:101]
	global_store_dwordx2 v[100:101], v[98:99], off
.LBB0_376:
	s_or_b64 exec, exec, s[26:27]
	v_pk_add_f32 v[98:99], v[174:175], v[176:177]
	s_mov_b32 s2, 0x3a800000
	v_pk_mul_f32 v[122:123], v[98:99], s[2:3] op_sel_hi:[1,0]
	s_mov_b32 s2, 0x800000
	v_fma_f32 v0, -v123, v123, v122
	v_max_f32_e32 v0, 0, v0
	v_add_f32_e32 v0, 0x3727c5ac, v0
	v_cmp_gt_f32_e32 vcc, s2, v0
	v_mul_f32_e32 v98, 0x4b800000, v0
	v_lshlrev_b64 v[124:125], 12, v[170:171]
	v_cndmask_b32_e32 v0, v0, v98, vcc
	v_rsq_f32_e32 v0, v0
	s_load_dwordx16 s[60:75], s[34:35], 0x38
	v_lshlrev_b32_e32 v122, 6, v170
	v_mul_f32_e32 v98, 0x45800000, v0
	v_cndmask_b32_e32 v0, v0, v98, vcc
	v_lshl_add_u64 v[98:99], s[12:13], 0, v[124:125]
	v_lshl_add_u64 v[102:103], v[98:99], 0, v[152:153]
	global_load_dwordx4 v[126:129], v[102:103], off offset:16
	global_load_dwordx4 v[130:133], v[102:103], off
	global_load_dwordx4 v[134:137], v[154:155], off offset:16
	global_load_dwordx4 v[172:175], v[154:155], off
	global_load_dwordx4 v[176:179], v[156:157], off offset:16
	global_load_dwordx4 v[186:189], v[156:157], off
	global_load_dwordx4 v[98:101], v[102:103], off offset:528
	global_load_dwordx4 v[118:121], v[102:103], off offset:512
	s_nop 0
	global_load_dwordx4 v[102:105], v[154:155], off offset:528
	global_load_dwordx4 v[110:113], v[154:155], off offset:512
	global_load_dwordx4 v[106:109], v[156:157], off offset:528
	global_load_dwordx4 v[114:117], v[156:157], off offset:512
	s_movk_i32 s2, 0x3bc0
	v_and_or_b32 v122, v122, s2, v194
	s_mov_b32 s2, 0x3fd744fd
	s_waitcnt lgkmcnt(0)
	v_lshl_add_u64 v[124:125], s[74:75], 0, v[124:125]
	v_lshl_add_u64 v[124:125], v[124:125], 0, v[152:153]
	v_lshlrev_b32_e32 v122, 1, v122
	s_waitcnt vmcnt(11)
	v_sub_f32_e32 v129, v129, v123
	s_waitcnt vmcnt(10)
	v_sub_f32_e32 v133, v133, v123
	v_sub_f32_e32 v132, v132, v123
	v_sub_f32_e32 v131, v131, v123
	v_sub_f32_e32 v130, v130, v123
	v_sub_f32_e32 v128, v128, v123
	v_sub_f32_e32 v127, v127, v123
	v_sub_f32_e32 v126, v126, v123
	v_pk_mul_f32 v[130:131], v[0:1], v[130:131] op_sel_hi:[0,1]
	v_pk_mul_f32 v[132:133], v[0:1], v[132:133] op_sel_hi:[0,1]
	v_pk_mul_f32 v[126:127], v[0:1], v[126:127] op_sel_hi:[0,1]
	v_pk_mul_f32 v[128:129], v[0:1], v[128:129] op_sel_hi:[0,1]
	s_waitcnt vmcnt(6)
; __device__ __forceinline__ float xsum16(float v) { const auto r = __builtin_amdgcn_permlane16_swap(__float_as_uint(v), __float_as_uint(v), false, false); return __uint_as_float(r[0]) + __uint_as_float(r[1]); }
; __device__ __forceinline__ float xsum32(float v) { const auto r = __builtin_amdgcn_permlane32_swap(__float_as_uint(v), __float_as_uint(v), false, false); return __uint_as_float(r[0]) + __uint_as_float(r[1]); }
; __device__ __forceinline__ size_t blk_off(int r, int c, int K) { return (size_t)(r >> 8) * 256 * K + (size_t)(c >> 6) * (256 * 64) + (size_t)((r & 255) * 64 + (c & 63)); }
; __device__ __forceinline__ u32x4 pack8(const f32x4 a, const f32x4 b) { u32x4 w; w.x = cvt_pk_bf16(a[0], a[1]); w.y = cvt_pk_bf16(a[2], a[3]); w.z = cvt_pk_bf16(b[0], b[1]); w.w = cvt_pk_bf16(b[2], b[3]); return w; }
;     __device__ __forceinline__ void operator()(const f32x4 (&acc)[2][2][4][2], const pg8::Unit& u, int wr, int wc, int fr, int fq) const {
;     ...
;             for (int m = 0; m < 4; ++m) { const int row = row0 + ai * 128 + m * 16; const float mu = mu4[m], rs = rs4[m];
;                 f32x4 yv[2][2], gq[2][2], bq_[2][2];
; #pragma unroll
;                 for (int bj = 0; bj < 2; ++bj)
; #pragma unroll
;                     for (int n = 0; n < 2; ++n) { yv[bj][n] = *(const f32x4*)(Yin + (size_t)row * D_ + col0 + bj * 128 + 4 * n); gq[bj][n] = *(const f32x4*)(g + col0 + bj * 128 + 4 * n); bq_[bj][n] = *(const f32x4*)(b + col0 + bj * 128 + 4 * n); }
;                 asm volatile("" ::: "memory");
;                 float s1 = 0.f, s2 = 0.f;
; #pragma unroll
;                 for (int bj = 0; bj < 2; ++bj) { float* yp = Y + (size_t)row * D_ + col0 + bj * 128; f32x4 v[2];
; #pragma unroll
;                     for (int n = 0; n < 2; ++n) { v[n] = (((yv[bj][n] - mu) * rs) * gq[bj][n] + bq_[bj][n]) * ALPHA_ + acc[ai][bj][m][n] * sc;
;                         *(f32x4*)(yp + 4 * n) = v[n]; s1 += (v[n][0] + v[n][1]) + (v[n][2] + v[n][3]); s2 += (v[n][0] * v[n][0] + v[n][1] * v[n][1]) + (v[n][2] * v[n][2] + v[n][3] * v[n][3]); }
;                     *(u32x4*)(Yb + blk_off(row, col0 + bj * 128, D_)) = pack8(v[0], v[1]); }
;                 s1 = xsum32(xsum16(s1)); s2 = xsum32(xsum16(s2));
;                 if (fq == 0) *(f32x2*)(stn + (size_t)row * 32 + (u.pn * 4 + wc) * 2) = (f32x2){s1, s2}; asm volatile("" ::: "memory"); } }
	v_pk_fma_f32 v[132:133], v[174:175], v[132:133], v[188:189]
	v_pk_fma_f32 v[130:131], v[172:173], v[130:131], v[186:187]
	v_pk_fma_f32 v[128:129], v[136:137], v[128:129], v[178:179]
	v_pk_fma_f32 v[126:127], v[134:135], v[126:127], v[176:177]
	v_pk_mul_f32 v[130:131], v[130:131], s[2:3] op_sel_hi:[1,0]
	v_pk_mul_f32 v[132:133], v[132:133], s[2:3] op_sel_hi:[1,0]
	v_pk_mul_f32 v[126:127], v[126:127], s[2:3] op_sel_hi:[1,0]
	v_pk_mul_f32 v[128:129], v[128:129], s[2:3] op_sel_hi:[1,0]
	v_pk_fma_f32 v[96:97], v[96:97], 0.5, v[132:133] op_sel_hi:[1,0,1]
	v_pk_fma_f32 v[94:95], v[94:95], 0.5, v[130:131] op_sel_hi:[1,0,1]
	v_pk_fma_f32 v[92:93], v[92:93], 0.5, v[128:129] op_sel_hi:[1,0,1]
	v_pk_fma_f32 v[90:91], v[90:91], 0.5, v[126:127] op_sel_hi:[1,0,1]
	v_add_f32_e32 v130, v94, v95
	v_add_f32_e32 v131, v96, v97
	v_add_f32_e32 v126, v90, v91
	v_add_f32_e32 v127, v92, v93
	v_add_f32_e32 v130, v130, v131
	v_mul_f32_e32 v131, v95, v95
	v_mul_f32_e32 v132, v97, v97
	v_add_f32_e32 v126, v126, v127
	v_mul_f32_e32 v127, v91, v91
	v_mul_f32_e32 v128, v93, v93
	s_nop 0
	v_fmac_f32_e32 v131, v94, v94
	v_fmac_f32_e32 v132, v96, v96
	s_nop 1
	v_bfe_u32 v135, v227, 4, 1
	v_sub_u32_e32 v135, 0, v135
	v_lshlrev_b32_e32 v134, 4, v135
	v_lshl_add_u64 v[134:135], v[124:125], 0, v[134:135]
	v_permlane16_swap_b32_e32 v94, v90
	v_permlane16_swap_b32_e32 v95, v91
	v_permlane16_swap_b32_e32 v96, v92
	v_permlane16_swap_b32_e32 v97, v93
	global_store_dwordx4 v[134:135], v[94:97], off
	global_store_dwordx4 v[134:135], v[90:93], off offset:32
	s_nop 1
	v_permlane16_swap_b32_e32 v94, v90
	v_permlane16_swap_b32_e32 v95, v91
	v_permlane16_swap_b32_e32 v96, v92
	v_permlane16_swap_b32_e32 v97, v93
	v_fmac_f32_e32 v127, v90, v90
	v_fmac_f32_e32 v128, v92, v92
	v_cvt_pk_bf16_f32 v94, v94, v95
	v_cvt_pk_bf16_f32 v95, v96, v97
	v_cvt_pk_bf16_f32 v96, v90, v91
	v_cvt_pk_bf16_f32 v97, v92, v93
	s_waitcnt vmcnt(6)
	v_sub_f32_e32 v91, v121, v123
	v_sub_f32_e32 v90, v120, v123
	v_sub_f32_e32 v93, v119, v123
	v_sub_f32_e32 v92, v118, v123
	v_pk_mul_f32 v[92:93], v[0:1], v[92:93] op_sel_hi:[0,1]
	v_pk_mul_f32 v[90:91], v[0:1], v[90:91] op_sel_hi:[0,1]
	s_waitcnt vmcnt(2)
	v_pk_fma_f32 v[90:91], v[112:113], v[90:91], v[116:117]
	v_pk_fma_f32 v[92:93], v[110:111], v[92:93], v[114:115]
	v_pk_mul_f32 v[90:91], v[90:91], s[2:3] op_sel_hi:[1,0]
	v_pk_mul_f32 v[92:93], v[92:93], s[2:3] op_sel_hi:[1,0]
	v_pk_fma_f32 v[88:89], v[88:89], 0.5, v[90:91] op_sel_hi:[1,0,1]
	v_pk_fma_f32 v[86:87], v[86:87], 0.5, v[92:93] op_sel_hi:[1,0,1]
	v_add_f32_e32 v130, 0, v130
	v_add_f32_e32 v90, v86, v87
	v_add_f32_e32 v91, v88, v89
	v_add_f32_e32 v126, v130, v126
	v_add_f32_e32 v90, v90, v91
	global_store_dwordx4 v122, v[94:97], s[50:51]
	v_mul_f32_e32 v91, v89, v89
	v_add_f32_e32 v131, v131, v132
	v_add_f32_e32 v94, v126, v90
	v_mul_f32_e32 v90, v87, v87
	v_add_f32_e32 v127, v127, v128
	v_fmac_f32_e32 v90, v86, v86
	v_fmac_f32_e32 v91, v88, v88
	v_add_f32_e32 v127, v131, v127
	v_add_f32_e32 v90, v90, v91
	v_add_f32_e32 v95, v127, v90
	v_sub_f32_e32 v91, v101, v123
	v_sub_f32_e32 v90, v100, v123
	v_sub_f32_e32 v93, v99, v123
	v_sub_f32_e32 v92, v98, v123
	v_pk_mul_f32 v[92:93], v[0:1], v[92:93] op_sel_hi:[0,1]
	v_pk_mul_f32 v[90:91], v[0:1], v[90:91] op_sel_hi:[0,1]
	v_pk_fma_f32 v[90:91], v[104:105], v[90:91], v[108:109]
	v_pk_fma_f32 v[92:93], v[102:103], v[92:93], v[106:107]
	v_pk_mul_f32 v[90:91], v[90:91], s[2:3] op_sel_hi:[1,0]
	v_pk_mul_f32 v[92:93], v[92:93], s[2:3] op_sel_hi:[1,0]
	v_pk_fma_f32 v[84:85], v[84:85], 0.5, v[90:91] op_sel_hi:[1,0,1]
	v_pk_fma_f32 v[82:83], v[82:83], 0.5, v[92:93] op_sel_hi:[1,0,1]
	v_add_f32_e32 v90, v84, v85
	v_add_f32_e32 v0, v82, v83
	v_add_f32_e32 v0, v0, v90
	v_mul_f32_e32 v90, v83, v83
	v_mul_f32_e32 v91, v85, v85
	v_add_f32_e32 v0, v94, v0
	v_fmac_f32_e32 v90, v82, v82
	v_fmac_f32_e32 v91, v84, v84
	s_nop 0
	s_nop 1
	v_bfe_u32 v93, v227, 4, 1
	v_sub_u32_e32 v93, 0, v93
	v_lshlrev_b32_e32 v92, 4, v93
	v_lshl_add_u64 v[92:93], v[124:125], 0, v[92:93]
	v_permlane16_swap_b32_e32 v86, v82
	v_permlane16_swap_b32_e32 v87, v83
	v_permlane16_swap_b32_e32 v88, v84
	v_permlane16_swap_b32_e32 v89, v85
	global_store_dwordx4 v[92:93], v[86:89], off offset:512
	global_store_dwordx4 v[92:93], v[82:85], off offset:544
	s_nop 1
	v_permlane16_swap_b32_e32 v86, v82
	v_permlane16_swap_b32_e32 v87, v83
	v_permlane16_swap_b32_e32 v88, v84
	v_permlane16_swap_b32_e32 v89, v85
	v_add_f32_e32 v90, v90, v91
	v_cvt_pk_bf16_f32 v86, v86, v87
	v_cvt_pk_bf16_f32 v87, v88, v89
	v_cvt_pk_bf16_f32 v88, v82, v83
	v_mov_b32_e32 v82, v0
	v_add_f32_e32 v90, v95, v90
	s_nop 0
	v_permlane16_swap_b32_e32 v0, v82
	v_add_f32_e32 v82, v0, v82
	v_mov_b32_e32 v0, v90
	s_nop 1
	v_permlane16_swap_b32_e32 v90, v0
	v_add_f32_e32 v83, v90, v0
	v_cvt_pk_bf16_f32 v89, v84, v85
	v_mov_b32_e32 v84, v82
	v_mov_b32_e32 v85, v83
	s_nop 0
	v_permlane32_swap_b32_e32 v82, v84
	v_permlane32_swap_b32_e32 v83, v85
	global_store_dwordx4 v122, v[86:89], s[42:43]
	s_and_saveexec_b64 s[26:27], s[44:45]
	s_cbranch_execz .LBB0_378
	v_pk_add_f32 v[82:83], v[82:83], v[84:85]
	v_lshl_add_u64 v[84:85], s[30:31], 0, v[164:165]
	v_lshl_add_u64 v[84:85], s[24:25], 2, v[84:85]
	global_store_dwordx2 v[84:85], v[82:83], off
; __device__ __forceinline__ float xsum16(float v) { const auto r = __builtin_amdgcn_permlane16_swap(__float_as_uint(v), __float_as_uint(v), false, false); return __uint_as_float(r[0]) + __uint_as_float(r[1]); }
; __device__ __forceinline__ float xsum32(float v) { const auto r = __builtin_amdgcn_permlane32_swap(__float_as_uint(v), __float_as_uint(v), false, false); return __uint_as_float(r[0]) + __uint_as_float(r[1]); }
; __device__ __forceinline__ size_t blk_off(int r, int c, int K) { return (size_t)(r >> 8) * 256 * K + (size_t)(c >> 6) * (256 * 64) + (size_t)((r & 255) * 64 + (c & 63)); }
; __device__ __forceinline__ u32x4 pack8(const f32x4 a, const f32x4 b) { u32x4 w; w.x = cvt_pk_bf16(a[0], a[1]); w.y = cvt_pk_bf16(a[2], a[3]); w.z = cvt_pk_bf16(b[0], b[1]); w.w = cvt_pk_bf16(b[2], b[3]); return w; }
;     __device__ __forceinline__ void operator()(const f32x4 (&acc)[2][2][4][2], const pg8::Unit& u, int wr, int wc, int fr, int fq) const {
;     ...
;             for (int m = 0; m < 4; ++m) { const int row = row0 + ai * 128 + m * 16; const float mu = mu4[m], rs = rs4[m];
;                 f32x4 yv[2][2], gq[2][2], bq_[2][2];
; #pragma unroll
;                 for (int bj = 0; bj < 2; ++bj)
; #pragma unroll
;                     for (int n = 0; n < 2; ++n) { yv[bj][n] = *(const f32x4*)(Yin + (size_t)row * D_ + col0 + bj * 128 + 4 * n); gq[bj][n] = *(const f32x4*)(g + col0 + bj * 128 + 4 * n); bq_[bj][n] = *(const f32x4*)(b + col0 + bj * 128 + 4 * n); }
;                 asm volatile("" ::: "memory");
;                 float s1 = 0.f, s2 = 0.f;
; #pragma unroll
;                 for (int bj = 0; bj < 2; ++bj) { float* yp = Y + (size_t)row * D_ + col0 + bj * 128; f32x4 v[2];
; #pragma unroll
;                     for (int n = 0; n < 2; ++n) { v[n] = (((yv[bj][n] - mu) * rs) * gq[bj][n] + bq_[bj][n]) * ALPHA_ + acc[ai][bj][m][n] * sc;
;                         *(f32x4*)(yp + 4 * n) = v[n]; s1 += (v[n][0] + v[n][1]) + (v[n][2] + v[n][3]); s2 += (v[n][0] * v[n][0] + v[n][1] * v[n][1]) + (v[n][2] * v[n][2] + v[n][3] * v[n][3]); }
;                     *(u32x4*)(Yb + blk_off(row, col0 + bj * 128, D_)) = pack8(v[0], v[1]); }
;                 s1 = xsum32(xsum16(s1)); s2 = xsum32(xsum16(s2));
;                 if (fq == 0) *(f32x2*)(stn + (size_t)row * 32 + (u.pn * 4 + wc) * 2) = (f32x2){s1, s2}; asm volatile("" ::: "memory"); } }
.LBB0_378:
	s_or_b64 exec, exec, s[26:27]
	v_pk_add_f32 v[82:83], v[166:167], v[168:169]
	s_mov_b32 s2, 0x3a800000
	v_pk_mul_f32 v[106:107], v[82:83], s[2:3] op_sel_hi:[1,0]
	s_mov_b32 s2, 0x800000
	v_fma_f32 v0, -v107, v107, v106
	v_max_f32_e32 v0, 0, v0
	v_add_f32_e32 v0, 0x3727c5ac, v0
	v_cmp_gt_f32_e32 vcc, s2, v0
	v_mul_f32_e32 v82, 0x4b800000, v0
	v_lshlrev_b64 v[108:109], 12, v[162:163]
	v_cndmask_b32_e32 v0, v0, v82, vcc
	v_rsq_f32_e32 v0, v0
	s_load_dwordx16 s[60:75], s[34:35], 0x38
	v_lshlrev_b32_e32 v106, 6, v162
	v_mul_f32_e32 v82, 0x45800000, v0
	v_cndmask_b32_e32 v0, v0, v82, vcc
	v_lshl_add_u64 v[82:83], s[12:13], 0, v[108:109]
	v_lshl_add_u64 v[86:87], v[82:83], 0, v[152:153]
	global_load_dwordx4 v[110:113], v[86:87], off offset:16
	global_load_dwordx4 v[114:117], v[86:87], off
	global_load_dwordx4 v[118:121], v[154:155], off offset:16
	global_load_dwordx4 v[122:125], v[154:155], off
	global_load_dwordx4 v[126:129], v[156:157], off offset:16
	global_load_dwordx4 v[130:133], v[156:157], off
	global_load_dwordx4 v[82:85], v[86:87], off offset:528
	global_load_dwordx4 v[102:105], v[86:87], off offset:512
	s_nop 0
	global_load_dwordx4 v[86:89], v[154:155], off offset:528
	global_load_dwordx4 v[94:97], v[154:155], off offset:512
	global_load_dwordx4 v[90:93], v[156:157], off offset:528
	global_load_dwordx4 v[98:101], v[156:157], off offset:512
	s_movk_i32 s2, 0x3fc0
	v_and_or_b32 v106, v106, s2, v194
	s_mov_b32 s2, 0x3fd744fd
	s_waitcnt lgkmcnt(0)
	v_lshl_add_u64 v[108:109], s[74:75], 0, v[108:109]
	v_lshl_add_u64 v[108:109], v[108:109], 0, v[152:153]
	v_lshlrev_b32_e32 v106, 1, v106
	s_waitcnt vmcnt(11)
	v_sub_f32_e32 v113, v113, v107
	s_waitcnt vmcnt(10)
	v_sub_f32_e32 v117, v117, v107
	v_sub_f32_e32 v116, v116, v107
	v_sub_f32_e32 v115, v115, v107
	v_sub_f32_e32 v114, v114, v107
	v_sub_f32_e32 v112, v112, v107
	v_sub_f32_e32 v111, v111, v107
	v_sub_f32_e32 v110, v110, v107
	v_pk_mul_f32 v[114:115], v[0:1], v[114:115] op_sel_hi:[0,1]
	v_pk_mul_f32 v[116:117], v[0:1], v[116:117] op_sel_hi:[0,1]
	v_pk_mul_f32 v[110:111], v[0:1], v[110:111] op_sel_hi:[0,1]
	v_pk_mul_f32 v[112:113], v[0:1], v[112:113] op_sel_hi:[0,1]
	s_waitcnt vmcnt(6)
	v_pk_fma_f32 v[116:117], v[124:125], v[116:117], v[132:133]
	v_pk_fma_f32 v[114:115], v[122:123], v[114:115], v[130:131]
	v_pk_fma_f32 v[112:113], v[120:121], v[112:113], v[128:129]
	v_pk_fma_f32 v[110:111], v[118:119], v[110:111], v[126:127]
	v_pk_mul_f32 v[114:115], v[114:115], s[2:3] op_sel_hi:[1,0]
	v_pk_mul_f32 v[116:117], v[116:117], s[2:3] op_sel_hi:[1,0]
	v_pk_mul_f32 v[110:111], v[110:111], s[2:3] op_sel_hi:[1,0]
	v_pk_mul_f32 v[112:113], v[112:113], s[2:3] op_sel_hi:[1,0]
	v_pk_fma_f32 v[80:81], v[80:81], 0.5, v[116:117] op_sel_hi:[1,0,1]
	v_pk_fma_f32 v[78:79], v[78:79], 0.5, v[114:115] op_sel_hi:[1,0,1]
	v_pk_fma_f32 v[76:77], v[76:77], 0.5, v[112:113] op_sel_hi:[1,0,1]
	v_pk_fma_f32 v[74:75], v[74:75], 0.5, v[110:111] op_sel_hi:[1,0,1]
	v_add_f32_e32 v114, v78, v79
	v_add_f32_e32 v115, v80, v81
	v_add_f32_e32 v110, v74, v75
	v_add_f32_e32 v111, v76, v77
	v_add_f32_e32 v114, v114, v115
	v_mul_f32_e32 v115, v79, v79
	v_mul_f32_e32 v116, v81, v81
	v_add_f32_e32 v110, v110, v111
	v_mul_f32_e32 v111, v75, v75
	v_mul_f32_e32 v112, v77, v77
	s_nop 0
	v_fmac_f32_e32 v115, v78, v78
	v_fmac_f32_e32 v116, v80, v80
	s_nop 1
	v_bfe_u32 v119, v227, 4, 1
	v_sub_u32_e32 v119, 0, v119
	v_lshlrev_b32_e32 v118, 4, v119
	v_lshl_add_u64 v[118:119], v[108:109], 0, v[118:119]
	v_permlane16_swap_b32_e32 v78, v74
	v_permlane16_swap_b32_e32 v79, v75
	v_permlane16_swap_b32_e32 v80, v76
	v_permlane16_swap_b32_e32 v81, v77
	global_store_dwordx4 v[118:119], v[78:81], off
	global_store_dwordx4 v[118:119], v[74:77], off offset:32
	s_nop 1
	v_permlane16_swap_b32_e32 v78, v74
	v_permlane16_swap_b32_e32 v79, v75
	v_permlane16_swap_b32_e32 v80, v76
	v_permlane16_swap_b32_e32 v81, v77
	v_fmac_f32_e32 v111, v74, v74
	v_fmac_f32_e32 v112, v76, v76
	v_cvt_pk_bf16_f32 v78, v78, v79
	v_cvt_pk_bf16_f32 v79, v80, v81
	v_cvt_pk_bf16_f32 v80, v74, v75
	v_cvt_pk_bf16_f32 v81, v76, v77
	s_waitcnt vmcnt(6)
	v_sub_f32_e32 v75, v105, v107
	v_sub_f32_e32 v74, v104, v107
	v_sub_f32_e32 v77, v103, v107
	v_sub_f32_e32 v76, v102, v107
	v_pk_mul_f32 v[76:77], v[0:1], v[76:77] op_sel_hi:[0,1]
	v_pk_mul_f32 v[74:75], v[0:1], v[74:75] op_sel_hi:[0,1]
	s_waitcnt vmcnt(2)
; __device__ __forceinline__ float xsum16(float v) { const auto r = __builtin_amdgcn_permlane16_swap(__float_as_uint(v), __float_as_uint(v), false, false); return __uint_as_float(r[0]) + __uint_as_float(r[1]); }
; __device__ __forceinline__ void row_stats4(const float* st, int rowb, int fq, float (&mu)[4], float (&rs)[4]) {
;     ...
;     for (int m = 0; m < 4; ++m) { const f32x4* p = (const f32x4*)(st + (size_t)(rowb + m * 16) * 32 + fq * 8); a[m] = p[0]; b[m] = p[1]; }
; #pragma unroll
;     for (int m = 0; m < 4; ++m) { float s1 = (a[m][0] + a[m][2]) + (b[m][0] + b[m][2]), s2 = (a[m][1] + a[m][3]) + (b[m][1] + b[m][3]);
;         s1 = xsum32(xsum16(s1)); s2 = xsum32(xsum16(s2));
;         const float mm = s1 * (1.0f / 1024.0f); mu[m] = mm; rs[m] = rsqrtf(fmaxf(s2 * (1.0f / 1024.0f) - mm * mm, 0.f) + LN_EPS_); }
;     __device__ __forceinline__ void operator()(const f32x4 (&acc)[2][2][4][2], const pg8::Unit& u, int wr, int wc, int fr, int fq) const {
;     ...
;             for (int m = 0; m < 4; ++m) { const int row = row0 + ai * 128 + m * 16; const float mu = mu4[m], rs = rs4[m];
;                 f32x4 yv[2][2], gq[2][2], bq_[2][2];
; #pragma unroll
;                 for (int bj = 0; bj < 2; ++bj)
; #pragma unroll
;                     for (int n = 0; n < 2; ++n) { yv[bj][n] = *(const f32x4*)(Yin + (size_t)row * D_ + col0 + bj * 128 + 4 * n); gq[bj][n] = *(const f32x4*)(g + col0 + bj * 128 + 4 * n); bq_[bj][n] = *(const f32x4*)(b + col0 + bj * 128 + 4 * n); }
;                 asm volatile("" ::: "memory");
;                 float s1 = 0.f, s2 = 0.f;
; #pragma unroll
;                 for (int bj = 0; bj < 2; ++bj) { float* yp = Y + (size_t)row * D_ + col0 + bj * 128; f32x4 v[2];
; #pragma unroll
;                     for (int n = 0; n < 2; ++n) { v[n] = (((yv[bj][n] - mu) * rs) * gq[bj][n] + bq_[bj][n]) * ALPHA_ + acc[ai][bj][m][n] * sc;
;                         *(f32x4*)(yp + 4 * n) = v[n]; s1 += (v[n][0] + v[n][1]) + (v[n][2] + v[n][3]); s2 += (v[n][0] * v[n][0] + v[n][1] * v[n][1]) + (v[n][2] * v[n][2] + v[n][3] * v[n][3]); }
;                     *(u32x4*)(Yb + blk_off(row, col0 + bj * 128, D_)) = pack8(v[0], v[1]); }
;                 s1 = xsum32(xsum16(s1)); s2 = xsum32(xsum16(s2));
;                 if (fq == 0) *(f32x2*)(stn + (size_t)row * 32 + (u.pn * 4 + wc) * 2) = (f32x2){s1, s2}; asm volatile("" ::: "memory"); } }
	v_pk_fma_f32 v[74:75], v[96:97], v[74:75], v[100:101]
	v_pk_fma_f32 v[76:77], v[94:95], v[76:77], v[98:99]
	v_pk_mul_f32 v[74:75], v[74:75], s[2:3] op_sel_hi:[1,0]
	v_pk_mul_f32 v[76:77], v[76:77], s[2:3] op_sel_hi:[1,0]
	v_pk_fma_f32 v[72:73], v[72:73], 0.5, v[74:75] op_sel_hi:[1,0,1]
	v_pk_fma_f32 v[70:71], v[70:71], 0.5, v[76:77] op_sel_hi:[1,0,1]
	v_add_f32_e32 v114, 0, v114
	v_add_f32_e32 v74, v70, v71
	v_add_f32_e32 v75, v72, v73
	v_add_f32_e32 v110, v114, v110
	v_add_f32_e32 v74, v74, v75
	global_store_dwordx4 v106, v[78:81], s[50:51]
	v_mul_f32_e32 v75, v73, v73
	v_add_f32_e32 v115, v115, v116
	v_add_f32_e32 v78, v110, v74
	v_mul_f32_e32 v74, v71, v71
	v_add_f32_e32 v111, v111, v112
	v_fmac_f32_e32 v74, v70, v70
	v_fmac_f32_e32 v75, v72, v72
	v_add_f32_e32 v111, v115, v111
	v_add_f32_e32 v74, v74, v75
	v_add_f32_e32 v79, v111, v74
	v_sub_f32_e32 v75, v85, v107
	v_sub_f32_e32 v74, v84, v107
	v_sub_f32_e32 v77, v83, v107
	v_sub_f32_e32 v76, v82, v107
	v_pk_mul_f32 v[76:77], v[0:1], v[76:77] op_sel_hi:[0,1]
	v_pk_mul_f32 v[74:75], v[0:1], v[74:75] op_sel_hi:[0,1]
	v_pk_fma_f32 v[74:75], v[88:89], v[74:75], v[92:93]
	v_pk_fma_f32 v[76:77], v[86:87], v[76:77], v[90:91]
	v_pk_mul_f32 v[74:75], v[74:75], s[2:3] op_sel_hi:[1,0]
	v_pk_mul_f32 v[76:77], v[76:77], s[2:3] op_sel_hi:[1,0]
	v_pk_fma_f32 v[68:69], v[68:69], 0.5, v[74:75] op_sel_hi:[1,0,1]
	v_pk_fma_f32 v[66:67], v[66:67], 0.5, v[76:77] op_sel_hi:[1,0,1]
	v_add_f32_e32 v74, v68, v69
	v_add_f32_e32 v0, v66, v67
	v_add_f32_e32 v0, v0, v74
	v_mul_f32_e32 v74, v67, v67
	v_mul_f32_e32 v75, v69, v69
	v_add_f32_e32 v0, v78, v0
	v_fmac_f32_e32 v74, v66, v66
	v_fmac_f32_e32 v75, v68, v68
	s_nop 0
	s_nop 1
	v_bfe_u32 v77, v227, 4, 1
	v_sub_u32_e32 v77, 0, v77
	v_lshlrev_b32_e32 v76, 4, v77
	v_lshl_add_u64 v[76:77], v[108:109], 0, v[76:77]
	v_permlane16_swap_b32_e32 v70, v66
	v_permlane16_swap_b32_e32 v71, v67
	v_permlane16_swap_b32_e32 v72, v68
	v_permlane16_swap_b32_e32 v73, v69
	global_store_dwordx4 v[76:77], v[70:73], off offset:512
	global_store_dwordx4 v[76:77], v[66:69], off offset:544
	s_nop 1
	v_permlane16_swap_b32_e32 v70, v66
	v_permlane16_swap_b32_e32 v71, v67
	v_permlane16_swap_b32_e32 v72, v68
	v_permlane16_swap_b32_e32 v73, v69
	v_add_f32_e32 v74, v74, v75
	v_cvt_pk_bf16_f32 v70, v70, v71
	v_cvt_pk_bf16_f32 v71, v72, v73
	v_cvt_pk_bf16_f32 v72, v66, v67
	v_mov_b32_e32 v66, v0
	v_add_f32_e32 v74, v79, v74
	s_nop 0
	v_permlane16_swap_b32_e32 v0, v66
	v_add_f32_e32 v66, v0, v66
	v_mov_b32_e32 v0, v74
	s_nop 1
	v_permlane16_swap_b32_e32 v74, v0
	v_add_f32_e32 v67, v74, v0
	v_cvt_pk_bf16_f32 v73, v68, v69
	v_mov_b32_e32 v68, v66
	v_mov_b32_e32 v69, v67
	s_nop 0
	v_permlane32_swap_b32_e32 v66, v68
	v_permlane32_swap_b32_e32 v67, v69
	global_store_dwordx4 v106, v[70:73], s[42:43]
	s_and_saveexec_b64 s[26:27], s[44:45]
	s_cbranch_execz .LBB0_380
	v_pk_add_f32 v[66:67], v[66:67], v[68:69]
	v_lshl_add_u64 v[68:69], s[30:31], 0, v[160:161]
	v_lshl_add_u64 v[68:69], s[24:25], 2, v[68:69]
	global_store_dwordx2 v[68:69], v[66:67], off
.LBB0_380:
	s_or_b64 exec, exec, s[26:27]
	v_add_u32_e32 v68, 0x80, v158
	v_ashrrev_i32_e32 v69, 31, v68
	v_add_u32_e32 v94, 0x90, v158
	v_lshlrev_b64 v[66:67], 7, v[68:69]
	v_ashrrev_i32_e32 v95, 31, v94
	v_lshl_add_u64 v[74:75], v[146:147], 0, v[66:67]
	v_lshlrev_b64 v[86:87], 7, v[94:95]
	v_add_u32_e32 v76, 0xa0, v158
	global_load_dwordx4 v[70:73], v[74:75], off
	global_load_dwordx4 v[78:81], v[74:75], off offset:16
	v_lshl_add_u64 v[74:75], v[146:147], 0, v[86:87]
	v_ashrrev_i32_e32 v77, 31, v76
	global_load_dwordx4 v[82:85], v[74:75], off
	global_load_dwordx4 v[88:91], v[74:75], off offset:16
	v_lshlrev_b64 v[74:75], 7, v[76:77]
	v_lshl_add_u64 v[74:75], v[146:147], 0, v[74:75]
	global_load_dwordx4 v[96:99], v[74:75], off
	global_load_dwordx4 v[100:103], v[74:75], off offset:16
	v_add_u32_e32 v74, 0xb0, v158
	v_ashrrev_i32_e32 v75, 31, v74
	v_lshlrev_b64 v[92:93], 7, v[74:75]
	v_lshl_add_u64 v[92:93], v[146:147], 0, v[92:93]
	global_load_dwordx4 v[104:107], v[92:93], off
	global_load_dwordx4 v[108:111], v[92:93], off offset:16
	v_lshlrev_b64 v[136:137], 12, v[68:69]
	v_lshl_add_u64 v[112:113], s[12:13], 0, v[136:137]
	v_lshl_add_u64 v[92:93], v[112:113], 0, v[152:153]
	global_load_dwordx4 v[112:115], v[92:93], off offset:16
	global_load_dwordx4 v[116:119], v[92:93], off
	global_load_dwordx4 v[120:123], v[154:155], off offset:16
	global_load_dwordx4 v[124:127], v[154:155], off
	global_load_dwordx4 v[128:131], v[156:157], off offset:16
	global_load_dwordx4 v[132:135], v[156:157], off
	s_mov_b32 s2, 0x3a800000
	s_mov_b32 s16, 0x3fd744fd
	s_load_dwordx16 s[60:75], s[34:35], 0x38
	s_waitcnt vmcnt(13)
	v_mov_b32_e32 v158, v70
	s_waitcnt vmcnt(12)
	v_mov_b32_e32 v159, v78
	v_mov_b32_e32 v160, v72
	v_mov_b32_e32 v161, v80
	v_mov_b32_e32 v78, v71
	v_mov_b32_e32 v80, v73
	s_waitcnt vmcnt(11)
	v_mov_b32_e32 v70, v82
	s_waitcnt vmcnt(10)
	v_mov_b32_e32 v71, v88
	v_mov_b32_e32 v72, v84
	v_mov_b32_e32 v73, v90
	v_mov_b32_e32 v88, v83
	v_mov_b32_e32 v90, v85
	s_waitcnt vmcnt(9)
	v_mov_b32_e32 v82, v96
	s_waitcnt vmcnt(8)
; __device__ __forceinline__ float xsum16(float v) { const auto r = __builtin_amdgcn_permlane16_swap(__float_as_uint(v), __float_as_uint(v), false, false); return __uint_as_float(r[0]) + __uint_as_float(r[1]); }
; __device__ __forceinline__ void row_stats4(const float* st, int rowb, int fq, float (&mu)[4], float (&rs)[4]) {
;     ...
;     for (int m = 0; m < 4; ++m) { const f32x4* p = (const f32x4*)(st + (size_t)(rowb + m * 16) * 32 + fq * 8); a[m] = p[0]; b[m] = p[1]; }
; #pragma unroll
;     for (int m = 0; m < 4; ++m) { float s1 = (a[m][0] + a[m][2]) + (b[m][0] + b[m][2]), s2 = (a[m][1] + a[m][3]) + (b[m][1] + b[m][3]);
;         s1 = xsum32(xsum16(s1)); s2 = xsum32(xsum16(s2));
;         const float mm = s1 * (1.0f / 1024.0f); mu[m] = mm; rs[m] = rsqrtf(fmaxf(s2 * (1.0f / 1024.0f) - mm * mm, 0.f) + LN_EPS_); }
;     __device__ __forceinline__ void operator()(const f32x4 (&acc)[2][2][4][2], const pg8::Unit& u, int wr, int wc, int fr, int fq) const {
;     ...
;             for (int m = 0; m < 4; ++m) { const int row = row0 + ai * 128 + m * 16; const float mu = mu4[m], rs = rs4[m];
;                 f32x4 yv[2][2], gq[2][2], bq_[2][2];
; #pragma unroll
;                 for (int bj = 0; bj < 2; ++bj)
; #pragma unroll
;                     for (int n = 0; n < 2; ++n) { yv[bj][n] = *(const f32x4*)(Yin + (size_t)row * D_ + col0 + bj * 128 + 4 * n); gq[bj][n] = *(const f32x4*)(g + col0 + bj * 128 + 4 * n); bq_[bj][n] = *(const f32x4*)(b + col0 + bj * 128 + 4 * n); }
;                 asm volatile("" ::: "memory");
;                 float s1 = 0.f, s2 = 0.f;
; #pragma unroll
;                 for (int bj = 0; bj < 2; ++bj) { float* yp = Y + (size_t)row * D_ + col0 + bj * 128; f32x4 v[2];
; #pragma unroll
;                     for (int n = 0; n < 2; ++n) { v[n] = (((yv[bj][n] - mu) * rs) * gq[bj][n] + bq_[bj][n]) * ALPHA_ + acc[ai][bj][m][n] * sc;
;                         *(f32x4*)(yp + 4 * n) = v[n]; s1 += (v[n][0] + v[n][1]) + (v[n][2] + v[n][3]); s2 += (v[n][0] * v[n][0] + v[n][1] * v[n][1]) + (v[n][2] * v[n][2] + v[n][3] * v[n][3]); }
;                     *(u32x4*)(Yb + blk_off(row, col0 + bj * 128, D_)) = pack8(v[0], v[1]); }
;                 s1 = xsum32(xsum16(s1)); s2 = xsum32(xsum16(s2));
;                 if (fq == 0) *(f32x2*)(stn + (size_t)row * 32 + (u.pn * 4 + wc) * 2) = (f32x2){s1, s2}; asm volatile("" ::: "memory"); } }
	v_mov_b32_e32 v83, v100
	v_mov_b32_e32 v84, v98
	v_mov_b32_e32 v85, v102
	v_mov_b32_e32 v100, v97
	v_pk_add_f32 v[96:97], v[158:159], v[160:161]
	v_pk_add_f32 v[78:79], v[78:79], v[80:81]
	v_pk_add_f32 v[80:81], v[82:83], v[84:85]
	v_pk_add_f32 v[84:85], v[96:97], v[96:97] op_sel:[0,1] op_sel_hi:[1,0]
	v_pk_add_f32 v[78:79], v[78:79], v[78:79] op_sel:[0,1] op_sel_hi:[1,0]
	v_mov_b32_e32 v0, v84
	v_mov_b32_e32 v69, v78
	s_nop 0
	v_permlane16_swap_b32_e32 v84, v0
	v_permlane16_swap_b32_e32 v78, v69
	v_add_f32_e32 v79, v84, v0
	v_add_f32_e32 v78, v78, v69
	v_mov_b32_e32 v85, v79
	v_mov_b32_e32 v84, v78
	s_nop 0
	v_permlane32_swap_b32_e32 v79, v85
	v_permlane32_swap_b32_e32 v78, v84
	v_pk_add_f32 v[78:79], v[78:79], v[84:85]
	v_mov_b32_e32 v102, v99
	v_pk_mul_f32 v[78:79], v[78:79], s[2:3] op_sel_hi:[1,0]
	s_mov_b32 s2, 0x800000
	v_fma_f32 v0, -v79, v79, v78
	v_max_f32_e32 v0, 0, v0
	v_add_f32_e32 v0, 0x3727c5ac, v0
	v_mul_f32_e32 v69, 0x4b800000, v0
	v_cmp_gt_f32_e32 vcc, s2, v0
	v_pk_add_f32 v[82:83], v[100:101], v[102:103]
	v_pk_add_f32 v[80:81], v[80:81], v[80:81] op_sel:[0,1] op_sel_hi:[1,0]
	v_cndmask_b32_e32 v0, v0, v69, vcc
	v_rsq_f32_e32 v0, v0
	v_pk_add_f32 v[82:83], v[82:83], v[82:83] op_sel:[0,1] op_sel_hi:[1,0]
	v_mov_b32_e32 v81, v80
	s_nop 1
	v_permlane16_swap_b32_e32 v80, v81
	v_mul_f32_e32 v69, 0x45800000, v0
	v_cndmask_b32_e32 v78, v0, v69, vcc
	v_mov_b32_e32 v0, v82
	s_nop 1
	v_permlane16_swap_b32_e32 v82, v0
	global_load_dwordx4 v[96:99], v[92:93], off offset:528
	global_load_dwordx4 v[100:103], v[92:93], off offset:512
	v_pk_add_f32 v[70:71], v[70:71], v[72:73]
	v_pk_add_f32 v[72:73], v[88:89], v[90:91]
	v_add_f32_e32 v89, v80, v81
	v_add_f32_e32 v88, v82, v0
	s_waitcnt vmcnt(9)
	v_mov_b32_e32 v80, v104
	s_waitcnt vmcnt(8)
	v_mov_b32_e32 v81, v108
	v_mov_b32_e32 v82, v106
	v_mov_b32_e32 v83, v110
	v_mov_b32_e32 v108, v105
	v_mov_b32_e32 v110, v107
	v_pk_add_f32 v[80:81], v[80:81], v[82:83]
	v_pk_add_f32 v[82:83], v[108:109], v[110:111]
	global_load_dwordx4 v[104:107], v[154:155], off offset:528
	global_load_dwordx4 v[108:111], v[154:155], off offset:512
	global_load_dwordx4 v[158:161], v[156:157], off offset:528
	global_load_dwordx4 v[162:165], v[156:157], off offset:512
	s_waitcnt vmcnt(10)
	v_sub_f32_e32 v93, v119, v79
	v_sub_f32_e32 v92, v118, v79
	v_sub_f32_e32 v117, v117, v79
	v_sub_f32_e32 v116, v116, v79
	v_pk_mul_f32 v[116:117], v[78:79], v[116:117] op_sel_hi:[0,1]
	v_pk_mul_f32 v[92:93], v[78:79], v[92:93] op_sel_hi:[0,1]
	s_waitcnt vmcnt(6)
	v_pk_fma_f32 v[92:93], v[126:127], v[92:93], v[134:135]
	v_pk_fma_f32 v[116:117], v[124:125], v[116:117], v[132:133]
	v_pk_mul_f32 v[92:93], v[92:93], s[16:17] op_sel_hi:[1,0]
	v_pk_mul_f32 v[116:117], v[116:117], s[16:17] op_sel_hi:[1,0]
	v_pk_fma_f32 v[64:65], v[64:65], 0.5, v[92:93] op_sel_hi:[1,0,1]
	v_pk_fma_f32 v[62:63], v[62:63], 0.5, v[116:117] op_sel_hi:[1,0,1]
	v_add_f32_e32 v93, v64, v65
	v_add_f32_e32 v92, v62, v63
	v_add_f32_e32 v92, v92, v93
	v_add_f32_e32 v116, 0, v92
	v_mul_f32_e32 v92, v63, v63
	v_mul_f32_e32 v93, v65, v65
	v_pk_add_f32 v[80:81], v[80:81], v[80:81] op_sel:[0,1] op_sel_hi:[1,0]
	v_fmac_f32_e32 v92, v62, v62
	v_fmac_f32_e32 v93, v64, v64
	v_mov_b32_e32 v0, v80
	v_add_f32_e32 v117, v92, v93
	v_sub_f32_e32 v93, v115, v79
	v_sub_f32_e32 v92, v114, v79
	v_sub_f32_e32 v113, v113, v79
	v_sub_f32_e32 v112, v112, v79
	v_pk_add_f32 v[82:83], v[82:83], v[82:83] op_sel:[0,1] op_sel_hi:[1,0]
	v_permlane16_swap_b32_e32 v80, v0
	v_pk_mul_f32 v[112:113], v[78:79], v[112:113] op_sel_hi:[0,1]
	v_pk_mul_f32 v[92:93], v[78:79], v[92:93] op_sel_hi:[0,1]
	v_add_f32_e32 v83, v80, v0
	v_mov_b32_e32 v0, v82
	v_pk_fma_f32 v[92:93], v[122:123], v[92:93], v[130:131]
	v_pk_fma_f32 v[112:113], v[120:121], v[112:113], v[128:129]
	v_permlane16_swap_b32_e32 v82, v0
	v_pk_mul_f32 v[112:113], v[112:113], s[16:17] op_sel_hi:[1,0]
	v_pk_mul_f32 v[92:93], v[92:93], s[16:17] op_sel_hi:[1,0]
	v_add_f32_e32 v82, v82, v0
	v_ashrrev_i32_e32 v80, 8, v68
	v_lshlrev_b32_e32 v0, 6, v68
	s_movk_i32 s2, 0x33c0
	v_pk_fma_f32 v[60:61], v[60:61], 0.5, v[92:93] op_sel_hi:[1,0,1]
	v_pk_fma_f32 v[58:59], v[58:59], 0.5, v[112:113] op_sel_hi:[1,0,1]
	v_ashrrev_i32_e32 v81, 31, v80
	v_and_or_b32 v0, v0, s2, v194
	s_waitcnt lgkmcnt(0)
	v_lshl_add_u64 v[68:69], s[74:75], 0, v[136:137]
	v_add_f32_e32 v92, v58, v59
	v_add_f32_e32 v93, v60, v61
	v_readlane_b32 s2, v253, 59
	v_lshlrev_b64 v[80:81], 19, v[80:81]
	v_lshl_add_u64 v[68:69], v[68:69], 0, v[152:153]
	v_add_f32_e32 v92, v92, v93
	v_mul_f32_e32 v93, v59, v59
	v_readlane_b32 s3, v253, 60
	s_nop 0
	s_nop 1
	v_bfe_u32 v85, v227, 4, 1
	v_sub_u32_e32 v85, 0, v85
	v_lshlrev_b32_e32 v84, 4, v85
	v_lshl_add_u64 v[84:85], v[68:69], 0, v[84:85]
	v_permlane16_swap_b32_e32 v62, v58
	v_permlane16_swap_b32_e32 v63, v59
	v_permlane16_swap_b32_e32 v64, v60
	v_permlane16_swap_b32_e32 v65, v61
	global_store_dwordx4 v[84:85], v[62:65], off
	global_store_dwordx4 v[84:85], v[58:61], off offset:32
	s_nop 1
	v_permlane16_swap_b32_e32 v62, v58
	v_permlane16_swap_b32_e32 v63, v59
	v_permlane16_swap_b32_e32 v64, v60
	v_permlane16_swap_b32_e32 v65, v61
	v_fmac_f32_e32 v93, v58, v58
	v_cvt_pk_bf16_f32 v62, v62, v63
	v_cvt_pk_bf16_f32 v63, v64, v65
	v_cvt_pk_bf16_f32 v64, v58, v59
	v_lshl_add_u64 v[58:59], s[2:3], 0, v[80:81]
	v_mul_f32_e32 v112, v61, v61
	v_lshl_add_u64 v[80:81], v[58:59], 0, s[28:29]
	v_lshlrev_b32_e32 v0, 1, v0
	v_fmac_f32_e32 v112, v60, v60
	v_cvt_pk_bf16_f32 v65, v60, v61
	v_lshl_add_u64 v[60:61], v[80:81], 0, v[0:1]
	global_store_dwordx4 v[60:61], v[62:65], off
	s_waitcnt vmcnt(7)
; __device__ __forceinline__ float xsum16(float v) { const auto r = __builtin_amdgcn_permlane16_swap(__float_as_uint(v), __float_as_uint(v), false, false); return __uint_as_float(r[0]) + __uint_as_float(r[1]); }
; __device__ __forceinline__ float xsum32(float v) { const auto r = __builtin_amdgcn_permlane32_swap(__float_as_uint(v), __float_as_uint(v), false, false); return __uint_as_float(r[0]) + __uint_as_float(r[1]); }
; __device__ __forceinline__ size_t blk_off(int r, int c, int K) { return (size_t)(r >> 8) * 256 * K + (size_t)(c >> 6) * (256 * 64) + (size_t)((r & 255) * 64 + (c & 63)); }
; __device__ __forceinline__ u32x4 pack8(const f32x4 a, const f32x4 b) { u32x4 w; w.x = cvt_pk_bf16(a[0], a[1]); w.y = cvt_pk_bf16(a[2], a[3]); w.z = cvt_pk_bf16(b[0], b[1]); w.w = cvt_pk_bf16(b[2], b[3]); return w; }
;     __device__ __forceinline__ void operator()(const f32x4 (&acc)[2][2][4][2], const pg8::Unit& u, int wr, int wc, int fr, int fq) const {
;     ...
;             for (int m = 0; m < 4; ++m) { const int row = row0 + ai * 128 + m * 16; const float mu = mu4[m], rs = rs4[m];
;                 f32x4 yv[2][2], gq[2][2], bq_[2][2];
; #pragma unroll
;                 for (int bj = 0; bj < 2; ++bj)
; #pragma unroll
;                     for (int n = 0; n < 2; ++n) { yv[bj][n] = *(const f32x4*)(Yin + (size_t)row * D_ + col0 + bj * 128 + 4 * n); gq[bj][n] = *(const f32x4*)(g + col0 + bj * 128 + 4 * n); bq_[bj][n] = *(const f32x4*)(b + col0 + bj * 128 + 4 * n); }
;                 asm volatile("" ::: "memory");
;                 float s1 = 0.f, s2 = 0.f;
; #pragma unroll
;                 for (int bj = 0; bj < 2; ++bj) { float* yp = Y + (size_t)row * D_ + col0 + bj * 128; f32x4 v[2];
; #pragma unroll
;                     for (int n = 0; n < 2; ++n) { v[n] = (((yv[bj][n] - mu) * rs) * gq[bj][n] + bq_[bj][n]) * ALPHA_ + acc[ai][bj][m][n] * sc;
;                         *(f32x4*)(yp + 4 * n) = v[n]; s1 += (v[n][0] + v[n][1]) + (v[n][2] + v[n][3]); s2 += (v[n][0] * v[n][0] + v[n][1] * v[n][1]) + (v[n][2] * v[n][2] + v[n][3] * v[n][3]); }
;                     *(u32x4*)(Yb + blk_off(row, col0 + bj * 128, D_)) = pack8(v[0], v[1]); }
;                 s1 = xsum32(xsum16(s1)); s2 = xsum32(xsum16(s2));
;                 if (fq == 0) *(f32x2*)(stn + (size_t)row * 32 + (u.pn * 4 + wc) * 2) = (f32x2){s1, s2}; asm volatile("" ::: "memory"); } }
	v_sub_f32_e32 v61, v103, v79
	v_sub_f32_e32 v60, v102, v79
	v_sub_f32_e32 v63, v101, v79
	v_sub_f32_e32 v62, v100, v79
	v_pk_mul_f32 v[62:63], v[78:79], v[62:63] op_sel_hi:[0,1]
	v_pk_mul_f32 v[60:61], v[78:79], v[60:61] op_sel_hi:[0,1]
	v_add_f32_e32 v92, v116, v92
	s_waitcnt vmcnt(3)
	v_pk_fma_f32 v[60:61], v[110:111], v[60:61], v[164:165]
	v_pk_fma_f32 v[62:63], v[108:109], v[62:63], v[162:163]
	v_pk_mul_f32 v[60:61], v[60:61], s[16:17] op_sel_hi:[1,0]
	v_pk_mul_f32 v[62:63], v[62:63], s[16:17] op_sel_hi:[1,0]
	v_pk_fma_f32 v[56:57], v[56:57], 0.5, v[60:61] op_sel_hi:[1,0,1]
	v_pk_fma_f32 v[54:55], v[54:55], 0.5, v[62:63] op_sel_hi:[1,0,1]
	v_add_f32_e32 v61, v56, v57
	v_add_f32_e32 v60, v54, v55
	v_add_f32_e32 v60, v60, v61
	v_add_f32_e32 v64, v92, v60
	v_mul_f32_e32 v60, v55, v55
	v_mul_f32_e32 v61, v57, v57
	v_add_f32_e32 v93, v93, v112
	v_fmac_f32_e32 v60, v54, v54
	v_fmac_f32_e32 v61, v56, v56
	v_add_f32_e32 v93, v117, v93
	v_add_f32_e32 v60, v60, v61
	v_add_f32_e32 v65, v93, v60
	v_sub_f32_e32 v61, v99, v79
	v_sub_f32_e32 v60, v98, v79
	v_sub_f32_e32 v63, v97, v79
	v_sub_f32_e32 v62, v96, v79
	v_pk_mul_f32 v[62:63], v[78:79], v[62:63] op_sel_hi:[0,1]
	v_pk_mul_f32 v[60:61], v[78:79], v[60:61] op_sel_hi:[0,1]
	v_pk_fma_f32 v[60:61], v[106:107], v[60:61], v[160:161]
	v_pk_fma_f32 v[62:63], v[104:105], v[62:63], v[158:159]
	v_pk_mul_f32 v[60:61], v[60:61], s[16:17] op_sel_hi:[1,0]
	v_pk_mul_f32 v[62:63], v[62:63], s[16:17] op_sel_hi:[1,0]
	v_pk_fma_f32 v[52:53], v[52:53], 0.5, v[60:61] op_sel_hi:[1,0,1]
	v_pk_fma_f32 v[50:51], v[50:51], 0.5, v[62:63] op_sel_hi:[1,0,1]
	v_add_f32_e32 v61, v52, v53
	v_add_f32_e32 v60, v50, v51
	v_add_f32_e32 v60, v60, v61
	v_mul_f32_e32 v61, v51, v51
	v_mul_f32_e32 v62, v53, v53
	v_add_f32_e32 v60, v64, v60
	v_fmac_f32_e32 v61, v50, v50
	v_fmac_f32_e32 v62, v52, v52
	v_lshl_add_u64 v[78:79], v[58:59], 0, s[40:41]
	s_nop 0
	s_nop 1
	v_bfe_u32 v85, v227, 4, 1
	v_sub_u32_e32 v85, 0, v85
	v_lshlrev_b32_e32 v84, 4, v85
	v_lshl_add_u64 v[84:85], v[68:69], 0, v[84:85]
	v_permlane16_swap_b32_e32 v54, v50
	v_permlane16_swap_b32_e32 v55, v51
	v_permlane16_swap_b32_e32 v56, v52
	v_permlane16_swap_b32_e32 v57, v53
	global_store_dwordx4 v[84:85], v[54:57], off offset:512
	global_store_dwordx4 v[84:85], v[50:53], off offset:544
	s_nop 1
	v_permlane16_swap_b32_e32 v54, v50
	v_permlane16_swap_b32_e32 v55, v51
	v_permlane16_swap_b32_e32 v56, v52
	v_permlane16_swap_b32_e32 v57, v53
	v_add_f32_e32 v61, v61, v62
	v_cvt_pk_bf16_f32 v54, v54, v55
	v_cvt_pk_bf16_f32 v55, v56, v57
	v_cvt_pk_bf16_f32 v56, v50, v51
	v_lshl_add_u64 v[50:51], v[78:79], 0, v[0:1]
	v_mov_b32_e32 v0, v60
	v_pk_add_f32 v[70:71], v[70:71], v[70:71] op_sel:[0,1] op_sel_hi:[1,0]
	v_pk_add_f32 v[72:73], v[72:73], v[72:73] op_sel:[0,1] op_sel_hi:[1,0]
	v_add_f32_e32 v61, v65, v61
	v_cvt_pk_bf16_f32 v57, v52, v53
	v_permlane16_swap_b32_e32 v60, v0
	v_mov_b32_e32 v71, v70
	v_mov_b32_e32 v73, v72
	global_store_dwordx4 v[50:51], v[54:57], off
	v_add_f32_e32 v50, v60, v0
	v_mov_b32_e32 v0, v61
	v_permlane16_swap_b32_e32 v70, v71
	v_permlane16_swap_b32_e32 v72, v73
	v_permlane16_swap_b32_e32 v61, v0
	v_add_f32_e32 v71, v70, v71
	v_add_f32_e32 v70, v72, v73
	v_add_f32_e32 v51, v61, v0
	v_mov_b32_e32 v73, v71
	v_mov_b32_e32 v72, v70
	v_mov_b32_e32 v91, v89
	v_mov_b32_e32 v90, v88
	v_mov_b32_e32 v85, v83
	v_mov_b32_e32 v84, v82
	v_mov_b32_e32 v52, v50
	v_mov_b32_e32 v53, v51
	v_permlane32_swap_b32_e32 v71, v73
	v_permlane32_swap_b32_e32 v70, v72
	v_permlane32_swap_b32_e32 v89, v91
	v_permlane32_swap_b32_e32 v88, v90
	v_permlane32_swap_b32_e32 v83, v85
	v_permlane32_swap_b32_e32 v82, v84
	v_permlane32_swap_b32_e32 v50, v52
	v_permlane32_swap_b32_e32 v51, v53
	s_and_saveexec_b64 s[26:27], s[44:45]
	s_cbranch_execz .LBB0_382
	v_pk_add_f32 v[50:51], v[50:51], v[52:53]
	v_lshl_add_u64 v[52:53], s[30:31], 0, v[66:67]
	v_lshl_add_u64 v[52:53], s[24:25], 2, v[52:53]
	global_store_dwordx2 v[52:53], v[50:51], off
.LBB0_382:
	s_or_b64 exec, exec, s[26:27]
	v_pk_add_f32 v[50:51], v[70:71], v[72:73]
	s_mov_b32 s2, 0x3a800000
	v_pk_mul_f32 v[92:93], v[50:51], s[2:3] op_sel_hi:[1,0]
	s_mov_b32 s2, 0x800000
	v_fma_f32 v0, -v93, v93, v92
	v_max_f32_e32 v0, 0, v0
	v_add_f32_e32 v0, 0x3727c5ac, v0
	v_cmp_gt_f32_e32 vcc, s2, v0
	v_mul_f32_e32 v50, 0x4b800000, v0
	v_lshlrev_b64 v[120:121], 12, v[94:95]
	v_cndmask_b32_e32 v0, v0, v50, vcc
	v_rsq_f32_e32 v0, v0
	s_movk_i32 s2, 0x37c0
	s_load_dwordx16 s[60:75], s[34:35], 0x38
	v_mul_f32_e32 v50, 0x45800000, v0
	v_cndmask_b32_e32 v92, v0, v50, vcc
	v_lshl_add_u64 v[50:51], s[12:13], 0, v[120:121]
	v_lshl_add_u64 v[54:55], v[50:51], 0, v[152:153]
	global_load_dwordx4 v[96:99], v[54:55], off offset:16
	global_load_dwordx4 v[100:103], v[54:55], off
	global_load_dwordx4 v[104:107], v[154:155], off offset:16
	global_load_dwordx4 v[108:111], v[154:155], off
	global_load_dwordx4 v[112:115], v[156:157], off offset:16
	global_load_dwordx4 v[116:119], v[156:157], off
	global_load_dwordx4 v[50:53], v[54:55], off offset:528
	global_load_dwordx4 v[70:73], v[54:55], off offset:512
	s_nop 0
	global_load_dwordx4 v[54:57], v[154:155], off offset:528
	global_load_dwordx4 v[62:65], v[154:155], off offset:512
	global_load_dwordx4 v[58:61], v[156:157], off offset:528
	global_load_dwordx4 v[66:69], v[156:157], off offset:512
	v_lshlrev_b32_e32 v0, 6, v94
	v_and_or_b32 v0, v0, s2, v194
	s_mov_b32 s2, 0x3fd744fd
	s_waitcnt lgkmcnt(0)
	v_lshl_add_u64 v[94:95], s[74:75], 0, v[120:121]
	v_lshlrev_b32_e32 v0, 1, v0
	v_lshl_add_u64 v[94:95], v[94:95], 0, v[152:153]
	s_waitcnt vmcnt(10)
; __device__ __forceinline__ float xsum16(float v) { const auto r = __builtin_amdgcn_permlane16_swap(__float_as_uint(v), __float_as_uint(v), false, false); return __uint_as_float(r[0]) + __uint_as_float(r[1]); }
; __device__ __forceinline__ float xsum32(float v) { const auto r = __builtin_amdgcn_permlane32_swap(__float_as_uint(v), __float_as_uint(v), false, false); return __uint_as_float(r[0]) + __uint_as_float(r[1]); }
; __device__ __forceinline__ size_t blk_off(int r, int c, int K) { return (size_t)(r >> 8) * 256 * K + (size_t)(c >> 6) * (256 * 64) + (size_t)((r & 255) * 64 + (c & 63)); }
; __device__ __forceinline__ u32x4 pack8(const f32x4 a, const f32x4 b) { u32x4 w; w.x = cvt_pk_bf16(a[0], a[1]); w.y = cvt_pk_bf16(a[2], a[3]); w.z = cvt_pk_bf16(b[0], b[1]); w.w = cvt_pk_bf16(b[2], b[3]); return w; }
;     __device__ __forceinline__ void operator()(const f32x4 (&acc)[2][2][4][2], const pg8::Unit& u, int wr, int wc, int fr, int fq) const {
;     ...
;             for (int m = 0; m < 4; ++m) { const int row = row0 + ai * 128 + m * 16; const float mu = mu4[m], rs = rs4[m];
;                 f32x4 yv[2][2], gq[2][2], bq_[2][2];
; #pragma unroll
;                 for (int bj = 0; bj < 2; ++bj)
; #pragma unroll
;                     for (int n = 0; n < 2; ++n) { yv[bj][n] = *(const f32x4*)(Yin + (size_t)row * D_ + col0 + bj * 128 + 4 * n); gq[bj][n] = *(const f32x4*)(g + col0 + bj * 128 + 4 * n); bq_[bj][n] = *(const f32x4*)(b + col0 + bj * 128 + 4 * n); }
;                 asm volatile("" ::: "memory");
;                 float s1 = 0.f, s2 = 0.f;
; #pragma unroll
;                 for (int bj = 0; bj < 2; ++bj) { float* yp = Y + (size_t)row * D_ + col0 + bj * 128; f32x4 v[2];
; #pragma unroll
;                     for (int n = 0; n < 2; ++n) { v[n] = (((yv[bj][n] - mu) * rs) * gq[bj][n] + bq_[bj][n]) * ALPHA_ + acc[ai][bj][m][n] * sc;
;                         *(f32x4*)(yp + 4 * n) = v[n]; s1 += (v[n][0] + v[n][1]) + (v[n][2] + v[n][3]); s2 += (v[n][0] * v[n][0] + v[n][1] * v[n][1]) + (v[n][2] * v[n][2] + v[n][3] * v[n][3]); }
;                     *(u32x4*)(Yb + blk_off(row, col0 + bj * 128, D_)) = pack8(v[0], v[1]); }
;                 s1 = xsum32(xsum16(s1)); s2 = xsum32(xsum16(s2));
;                 if (fq == 0) *(f32x2*)(stn + (size_t)row * 32 + (u.pn * 4 + wc) * 2) = (f32x2){s1, s2}; asm volatile("" ::: "memory"); } }
	v_sub_f32_e32 v103, v103, v93
	v_sub_f32_e32 v102, v102, v93
	v_sub_f32_e32 v101, v101, v93
	v_sub_f32_e32 v100, v100, v93
	v_pk_mul_f32 v[100:101], v[92:93], v[100:101] op_sel_hi:[0,1]
	v_pk_mul_f32 v[102:103], v[92:93], v[102:103] op_sel_hi:[0,1]
	s_waitcnt vmcnt(6)
	v_pk_fma_f32 v[102:103], v[110:111], v[102:103], v[118:119]
	v_pk_fma_f32 v[100:101], v[108:109], v[100:101], v[116:117]
	v_pk_mul_f32 v[102:103], v[102:103], s[2:3] op_sel_hi:[1,0]
	v_pk_mul_f32 v[100:101], v[100:101], s[2:3] op_sel_hi:[1,0]
	v_pk_fma_f32 v[102:103], v[48:49], 0.5, v[102:103] op_sel_hi:[1,0,1]
	v_pk_fma_f32 v[100:101], v[46:47], 0.5, v[100:101] op_sel_hi:[1,0,1]
	v_add_f32_e32 v47, v102, v103
	v_add_f32_e32 v46, v100, v101
	v_add_f32_e32 v46, v46, v47
	v_add_f32_e32 v108, 0, v46
	v_mul_f32_e32 v46, v101, v101
	v_mul_f32_e32 v47, v103, v103
	v_fmac_f32_e32 v46, v100, v100
	v_fmac_f32_e32 v47, v102, v102
	v_add_f32_e32 v109, v46, v47
	v_sub_f32_e32 v47, v99, v93
	v_sub_f32_e32 v46, v98, v93
	v_sub_f32_e32 v49, v97, v93
	v_sub_f32_e32 v48, v96, v93
	v_pk_mul_f32 v[48:49], v[92:93], v[48:49] op_sel_hi:[0,1]
	v_pk_mul_f32 v[46:47], v[92:93], v[46:47] op_sel_hi:[0,1]
	v_pk_fma_f32 v[46:47], v[106:107], v[46:47], v[114:115]
	v_pk_fma_f32 v[48:49], v[104:105], v[48:49], v[112:113]
	v_pk_mul_f32 v[46:47], v[46:47], s[2:3] op_sel_hi:[1,0]
	v_pk_mul_f32 v[48:49], v[48:49], s[2:3] op_sel_hi:[1,0]
	v_pk_fma_f32 v[98:99], v[44:45], 0.5, v[46:47] op_sel_hi:[1,0,1]
	v_pk_fma_f32 v[96:97], v[42:43], 0.5, v[48:49] op_sel_hi:[1,0,1]
	v_add_f32_e32 v43, v98, v99
	v_add_f32_e32 v42, v96, v97
	v_add_f32_e32 v42, v42, v43
	v_add_f32_e32 v47, v108, v42
	v_mul_f32_e32 v42, v97, v97
	v_mul_f32_e32 v43, v99, v99
	v_fmac_f32_e32 v42, v96, v96
	v_fmac_f32_e32 v43, v98, v98
	v_add_f32_e32 v42, v42, v43
	v_add_f32_e32 v46, v109, v42
	v_cvt_pk_bf16_f32 v42, v100, v101
	v_cvt_pk_bf16_f32 v43, v102, v103
	v_cvt_pk_bf16_f32 v44, v96, v97
	v_cvt_pk_bf16_f32 v45, v98, v99
	v_lshl_add_u64 v[48:49], v[80:81], 0, v[0:1]
	s_nop 0
	s_nop 1
	v_bfe_u32 v105, v227, 4, 1
	v_sub_u32_e32 v105, 0, v105
	v_lshlrev_b32_e32 v104, 4, v105
	v_lshl_add_u64 v[104:105], v[94:95], 0, v[104:105]
	v_permlane16_swap_b32_e32 v100, v96
	v_permlane16_swap_b32_e32 v101, v97
	v_permlane16_swap_b32_e32 v102, v98
	v_permlane16_swap_b32_e32 v103, v99
	global_store_dwordx4 v[104:105], v[100:103], off
	global_store_dwordx4 v[104:105], v[96:99], off offset:32
	s_nop 1
	v_permlane16_swap_b32_e32 v100, v96
	v_permlane16_swap_b32_e32 v101, v97
	v_permlane16_swap_b32_e32 v102, v98
	v_permlane16_swap_b32_e32 v103, v99
	global_store_dwordx4 v[48:49], v[42:45], off
	s_waitcnt vmcnt(7)
	s_nop 0
	v_sub_f32_e32 v43, v73, v93
	v_sub_f32_e32 v42, v72, v93
	v_sub_f32_e32 v45, v71, v93
	v_sub_f32_e32 v44, v70, v93
	v_pk_mul_f32 v[44:45], v[92:93], v[44:45] op_sel_hi:[0,1]
	v_pk_mul_f32 v[42:43], v[92:93], v[42:43] op_sel_hi:[0,1]
	s_waitcnt vmcnt(3)
	v_pk_fma_f32 v[42:43], v[64:65], v[42:43], v[68:69]
	v_pk_fma_f32 v[44:45], v[62:63], v[44:45], v[66:67]
	v_pk_mul_f32 v[42:43], v[42:43], s[2:3] op_sel_hi:[1,0]
	v_pk_mul_f32 v[44:45], v[44:45], s[2:3] op_sel_hi:[1,0]
	v_pk_fma_f32 v[40:41], v[40:41], 0.5, v[42:43] op_sel_hi:[1,0,1]
	v_pk_fma_f32 v[38:39], v[38:39], 0.5, v[44:45] op_sel_hi:[1,0,1]
	v_add_f32_e32 v43, v40, v41
	v_add_f32_e32 v42, v38, v39
	v_add_f32_e32 v42, v42, v43
	v_add_f32_e32 v47, v47, v42
	v_mul_f32_e32 v42, v39, v39
	v_mul_f32_e32 v43, v41, v41
	v_fmac_f32_e32 v42, v38, v38
	v_fmac_f32_e32 v43, v40, v40
	v_add_f32_e32 v42, v42, v43
	v_add_f32_e32 v46, v46, v42
	v_sub_f32_e32 v43, v53, v93
	v_sub_f32_e32 v42, v52, v93
	v_sub_f32_e32 v45, v51, v93
	v_sub_f32_e32 v44, v50, v93
	v_pk_mul_f32 v[44:45], v[92:93], v[44:45] op_sel_hi:[0,1]
	v_pk_mul_f32 v[42:43], v[92:93], v[42:43] op_sel_hi:[0,1]
	v_pk_fma_f32 v[42:43], v[56:57], v[42:43], v[60:61]
	v_pk_fma_f32 v[44:45], v[54:55], v[44:45], v[58:59]
	v_pk_mul_f32 v[42:43], v[42:43], s[2:3] op_sel_hi:[1,0]
	v_pk_mul_f32 v[44:45], v[44:45], s[2:3] op_sel_hi:[1,0]
	v_pk_fma_f32 v[36:37], v[36:37], 0.5, v[42:43] op_sel_hi:[1,0,1]
	v_pk_fma_f32 v[34:35], v[34:35], 0.5, v[44:45] op_sel_hi:[1,0,1]
	v_add_f32_e32 v43, v36, v37
	v_add_f32_e32 v42, v34, v35
	v_add_f32_e32 v42, v42, v43
	v_mul_f32_e32 v43, v35, v35
	v_mul_f32_e32 v44, v37, v37
	v_add_f32_e32 v42, v47, v42
	v_fmac_f32_e32 v43, v34, v34
	v_fmac_f32_e32 v44, v36, v36
	s_nop 0
	s_nop 1
	v_bfe_u32 v49, v227, 4, 1
	v_sub_u32_e32 v49, 0, v49
	v_lshlrev_b32_e32 v48, 4, v49
	v_lshl_add_u64 v[48:49], v[94:95], 0, v[48:49]
	v_permlane16_swap_b32_e32 v38, v34
	v_permlane16_swap_b32_e32 v39, v35
	v_permlane16_swap_b32_e32 v40, v36
	v_permlane16_swap_b32_e32 v41, v37
	global_store_dwordx4 v[48:49], v[38:41], off offset:512
	global_store_dwordx4 v[48:49], v[34:37], off offset:544
	s_nop 1
	v_permlane16_swap_b32_e32 v38, v34
	v_permlane16_swap_b32_e32 v39, v35
	v_permlane16_swap_b32_e32 v40, v36
	v_permlane16_swap_b32_e32 v41, v37
	v_add_f32_e32 v43, v43, v44
	v_cvt_pk_bf16_f32 v38, v38, v39
	v_cvt_pk_bf16_f32 v39, v40, v41
	v_cvt_pk_bf16_f32 v40, v34, v35
	v_lshl_add_u64 v[34:35], v[78:79], 0, v[0:1]
	v_mov_b32_e32 v0, v42
	v_add_f32_e32 v43, v46, v43
	v_cvt_pk_bf16_f32 v41, v36, v37
	v_permlane16_swap_b32_e32 v42, v0
	global_store_dwordx4 v[34:35], v[38:41], off
	v_add_f32_e32 v34, v42, v0
	v_mov_b32_e32 v0, v43
	s_nop 1
	v_permlane16_swap_b32_e32 v43, v0
	v_add_f32_e32 v35, v43, v0
	v_mov_b32_e32 v36, v34
	v_mov_b32_e32 v37, v35
	s_nop 0
	v_permlane32_swap_b32_e32 v34, v36
	v_permlane32_swap_b32_e32 v35, v37
	s_and_saveexec_b64 s[26:27], s[44:45]
	s_cbranch_execz .LBB0_384
	v_pk_add_f32 v[34:35], v[34:35], v[36:37]
	v_lshl_add_u64 v[36:37], s[30:31], 0, v[86:87]
	v_lshl_add_u64 v[36:37], s[24:25], 2, v[36:37]
	global_store_dwordx2 v[36:37], v[34:35], off
; __device__ __forceinline__ float xsum16(float v) { const auto r = __builtin_amdgcn_permlane16_swap(__float_as_uint(v), __float_as_uint(v), false, false); return __uint_as_float(r[0]) + __uint_as_float(r[1]); }
; __device__ __forceinline__ float xsum32(float v) { const auto r = __builtin_amdgcn_permlane32_swap(__float_as_uint(v), __float_as_uint(v), false, false); return __uint_as_float(r[0]) + __uint_as_float(r[1]); }
; __device__ __forceinline__ size_t blk_off(int r, int c, int K) { return (size_t)(r >> 8) * 256 * K + (size_t)(c >> 6) * (256 * 64) + (size_t)((r & 255) * 64 + (c & 63)); }
; __device__ __forceinline__ u32x4 pack8(const f32x4 a, const f32x4 b) { u32x4 w; w.x = cvt_pk_bf16(a[0], a[1]); w.y = cvt_pk_bf16(a[2], a[3]); w.z = cvt_pk_bf16(b[0], b[1]); w.w = cvt_pk_bf16(b[2], b[3]); return w; }
;     __device__ __forceinline__ void operator()(const f32x4 (&acc)[2][2][4][2], const pg8::Unit& u, int wr, int wc, int fr, int fq) const {
;     ...
;             for (int m = 0; m < 4; ++m) { const int row = row0 + ai * 128 + m * 16; const float mu = mu4[m], rs = rs4[m];
;                 f32x4 yv[2][2], gq[2][2], bq_[2][2];
; #pragma unroll
;                 for (int bj = 0; bj < 2; ++bj)
; #pragma unroll
;                     for (int n = 0; n < 2; ++n) { yv[bj][n] = *(const f32x4*)(Yin + (size_t)row * D_ + col0 + bj * 128 + 4 * n); gq[bj][n] = *(const f32x4*)(g + col0 + bj * 128 + 4 * n); bq_[bj][n] = *(const f32x4*)(b + col0 + bj * 128 + 4 * n); }
;                 asm volatile("" ::: "memory");
;                 float s1 = 0.f, s2 = 0.f;
; #pragma unroll
;                 for (int bj = 0; bj < 2; ++bj) { float* yp = Y + (size_t)row * D_ + col0 + bj * 128; f32x4 v[2];
; #pragma unroll
;                     for (int n = 0; n < 2; ++n) { v[n] = (((yv[bj][n] - mu) * rs) * gq[bj][n] + bq_[bj][n]) * ALPHA_ + acc[ai][bj][m][n] * sc;
;                         *(f32x4*)(yp + 4 * n) = v[n]; s1 += (v[n][0] + v[n][1]) + (v[n][2] + v[n][3]); s2 += (v[n][0] * v[n][0] + v[n][1] * v[n][1]) + (v[n][2] * v[n][2] + v[n][3] * v[n][3]); }
;                     *(u32x4*)(Yb + blk_off(row, col0 + bj * 128, D_)) = pack8(v[0], v[1]); }
;                 s1 = xsum32(xsum16(s1)); s2 = xsum32(xsum16(s2));
;                 if (fq == 0) *(f32x2*)(stn + (size_t)row * 32 + (u.pn * 4 + wc) * 2) = (f32x2){s1, s2}; asm volatile("" ::: "memory"); } }
.LBB0_384:
	s_or_b64 exec, exec, s[26:27]
	v_pk_add_f32 v[34:35], v[88:89], v[90:91]
	s_mov_b32 s2, 0x3a800000
	v_pk_mul_f32 v[58:59], v[34:35], s[2:3] op_sel_hi:[1,0]
	s_mov_b32 s2, 0x800000
	v_fma_f32 v0, -v59, v59, v58
	v_max_f32_e32 v0, 0, v0
	v_add_f32_e32 v0, 0x3727c5ac, v0
	v_cmp_gt_f32_e32 vcc, s2, v0
	v_mul_f32_e32 v34, 0x4b800000, v0
	v_lshlrev_b64 v[60:61], 12, v[76:77]
	v_cndmask_b32_e32 v0, v0, v34, vcc
	v_rsq_f32_e32 v0, v0
	s_movk_i32 s2, 0x3bc0
	s_load_dwordx16 s[60:75], s[34:35], 0x38
	v_mul_f32_e32 v34, 0x45800000, v0
	v_cndmask_b32_e32 v58, v0, v34, vcc
	v_lshl_add_u64 v[34:35], s[12:13], 0, v[60:61]
	v_lshl_add_u64 v[38:39], v[34:35], 0, v[152:153]
	global_load_dwordx4 v[62:65], v[38:39], off offset:16
	global_load_dwordx4 v[66:69], v[38:39], off
	global_load_dwordx4 v[70:73], v[154:155], off offset:16
	global_load_dwordx4 v[86:89], v[154:155], off
	global_load_dwordx4 v[90:93], v[156:157], off offset:16
	global_load_dwordx4 v[94:97], v[156:157], off
	global_load_dwordx4 v[34:37], v[38:39], off offset:528
	global_load_dwordx4 v[54:57], v[38:39], off offset:512
	s_nop 0
	global_load_dwordx4 v[38:41], v[154:155], off offset:528
	global_load_dwordx4 v[46:49], v[154:155], off offset:512
	global_load_dwordx4 v[42:45], v[156:157], off offset:528
	global_load_dwordx4 v[50:53], v[156:157], off offset:512
	v_lshlrev_b32_e32 v0, 6, v76
	v_and_or_b32 v0, v0, s2, v194
	s_mov_b32 s2, 0x3fd744fd
	s_waitcnt lgkmcnt(0)
	v_lshl_add_u64 v[60:61], s[74:75], 0, v[60:61]
	v_lshlrev_b32_e32 v0, 1, v0
	v_lshl_add_u64 v[60:61], v[60:61], 0, v[152:153]
	s_waitcnt vmcnt(10)
	v_sub_f32_e32 v69, v69, v59
	v_sub_f32_e32 v68, v68, v59
	v_sub_f32_e32 v67, v67, v59
	v_sub_f32_e32 v66, v66, v59
	v_pk_mul_f32 v[66:67], v[58:59], v[66:67] op_sel_hi:[0,1]
	v_pk_mul_f32 v[68:69], v[58:59], v[68:69] op_sel_hi:[0,1]
	s_waitcnt vmcnt(6)
	v_pk_fma_f32 v[68:69], v[88:89], v[68:69], v[96:97]
	v_pk_fma_f32 v[66:67], v[86:87], v[66:67], v[94:95]
	v_pk_mul_f32 v[68:69], v[68:69], s[2:3] op_sel_hi:[1,0]
	v_pk_mul_f32 v[66:67], v[66:67], s[2:3] op_sel_hi:[1,0]
	v_pk_fma_f32 v[68:69], v[32:33], 0.5, v[68:69] op_sel_hi:[1,0,1]
	v_pk_fma_f32 v[66:67], v[30:31], 0.5, v[66:67] op_sel_hi:[1,0,1]
	v_add_f32_e32 v31, v68, v69
	v_add_f32_e32 v30, v66, v67
	v_add_f32_e32 v30, v30, v31
	v_add_f32_e32 v86, 0, v30
	v_mul_f32_e32 v30, v67, v67
	v_mul_f32_e32 v31, v69, v69
	v_fmac_f32_e32 v30, v66, v66
	v_fmac_f32_e32 v31, v68, v68
	v_add_f32_e32 v87, v30, v31
	v_sub_f32_e32 v31, v65, v59
	v_sub_f32_e32 v30, v64, v59
	v_sub_f32_e32 v33, v63, v59
	v_sub_f32_e32 v32, v62, v59
	v_pk_mul_f32 v[32:33], v[58:59], v[32:33] op_sel_hi:[0,1]
	v_pk_mul_f32 v[30:31], v[58:59], v[30:31] op_sel_hi:[0,1]
	v_pk_fma_f32 v[30:31], v[72:73], v[30:31], v[92:93]
	v_pk_fma_f32 v[32:33], v[70:71], v[32:33], v[90:91]
	v_pk_mul_f32 v[30:31], v[30:31], s[2:3] op_sel_hi:[1,0]
	v_pk_mul_f32 v[32:33], v[32:33], s[2:3] op_sel_hi:[1,0]
	v_pk_fma_f32 v[64:65], v[28:29], 0.5, v[30:31] op_sel_hi:[1,0,1]
	v_pk_fma_f32 v[62:63], v[26:27], 0.5, v[32:33] op_sel_hi:[1,0,1]
	v_add_f32_e32 v27, v64, v65
	v_add_f32_e32 v26, v62, v63
	v_add_f32_e32 v26, v26, v27
	v_add_f32_e32 v31, v86, v26
	v_mul_f32_e32 v26, v63, v63
	v_mul_f32_e32 v27, v65, v65
	v_fmac_f32_e32 v26, v62, v62
	v_fmac_f32_e32 v27, v64, v64
	v_add_f32_e32 v26, v26, v27
	v_add_f32_e32 v30, v87, v26
	v_cvt_pk_bf16_f32 v26, v66, v67
	v_cvt_pk_bf16_f32 v27, v68, v69
	v_cvt_pk_bf16_f32 v28, v62, v63
	v_cvt_pk_bf16_f32 v29, v64, v65
	v_lshl_add_u64 v[32:33], v[80:81], 0, v[0:1]
	s_nop 0
	s_nop 1
	v_bfe_u32 v71, v227, 4, 1
	v_sub_u32_e32 v71, 0, v71
	v_lshlrev_b32_e32 v70, 4, v71
	v_lshl_add_u64 v[70:71], v[60:61], 0, v[70:71]
	v_permlane16_swap_b32_e32 v66, v62
	v_permlane16_swap_b32_e32 v67, v63
	v_permlane16_swap_b32_e32 v68, v64
	v_permlane16_swap_b32_e32 v69, v65
	global_store_dwordx4 v[70:71], v[66:69], off
	global_store_dwordx4 v[70:71], v[62:65], off offset:32
	s_nop 1
	v_permlane16_swap_b32_e32 v66, v62
	v_permlane16_swap_b32_e32 v67, v63
	v_permlane16_swap_b32_e32 v68, v64
	v_permlane16_swap_b32_e32 v69, v65
	global_store_dwordx4 v[32:33], v[26:29], off
	s_waitcnt vmcnt(7)
	s_nop 0
	v_sub_f32_e32 v27, v57, v59
	v_sub_f32_e32 v26, v56, v59
	v_sub_f32_e32 v29, v55, v59
	v_sub_f32_e32 v28, v54, v59
	v_pk_mul_f32 v[28:29], v[58:59], v[28:29] op_sel_hi:[0,1]
	v_pk_mul_f32 v[26:27], v[58:59], v[26:27] op_sel_hi:[0,1]
	s_waitcnt vmcnt(3)
; __device__ __forceinline__ float xsum16(float v) { const auto r = __builtin_amdgcn_permlane16_swap(__float_as_uint(v), __float_as_uint(v), false, false); return __uint_as_float(r[0]) + __uint_as_float(r[1]); }
; __device__ __forceinline__ float xsum32(float v) { const auto r = __builtin_amdgcn_permlane32_swap(__float_as_uint(v), __float_as_uint(v), false, false); return __uint_as_float(r[0]) + __uint_as_float(r[1]); }
; __device__ __forceinline__ size_t blk_off(int r, int c, int K) { return (size_t)(r >> 8) * 256 * K + (size_t)(c >> 6) * (256 * 64) + (size_t)((r & 255) * 64 + (c & 63)); }
; __device__ __forceinline__ u32x4 pack8(const f32x4 a, const f32x4 b) { u32x4 w; w.x = cvt_pk_bf16(a[0], a[1]); w.y = cvt_pk_bf16(a[2], a[3]); w.z = cvt_pk_bf16(b[0], b[1]); w.w = cvt_pk_bf16(b[2], b[3]); return w; }
;     __device__ __forceinline__ void operator()(const f32x4 (&acc)[2][2][4][2], const pg8::Unit& u, int wr, int wc, int fr, int fq) const {
;     ...
;             for (int m = 0; m < 4; ++m) { const int row = row0 + ai * 128 + m * 16; const float mu = mu4[m], rs = rs4[m];
;                 f32x4 yv[2][2], gq[2][2], bq_[2][2];
; #pragma unroll
;                 for (int bj = 0; bj < 2; ++bj)
; #pragma unroll
;                     for (int n = 0; n < 2; ++n) { yv[bj][n] = *(const f32x4*)(Yin + (size_t)row * D_ + col0 + bj * 128 + 4 * n); gq[bj][n] = *(const f32x4*)(g + col0 + bj * 128 + 4 * n); bq_[bj][n] = *(const f32x4*)(b + col0 + bj * 128 + 4 * n); }
;                 asm volatile("" ::: "memory");
;                 float s1 = 0.f, s2 = 0.f;
; #pragma unroll
;                 for (int bj = 0; bj < 2; ++bj) { float* yp = Y + (size_t)row * D_ + col0 + bj * 128; f32x4 v[2];
; #pragma unroll
;                     for (int n = 0; n < 2; ++n) { v[n] = (((yv[bj][n] - mu) * rs) * gq[bj][n] + bq_[bj][n]) * ALPHA_ + acc[ai][bj][m][n] * sc;
;                         *(f32x4*)(yp + 4 * n) = v[n]; s1 += (v[n][0] + v[n][1]) + (v[n][2] + v[n][3]); s2 += (v[n][0] * v[n][0] + v[n][1] * v[n][1]) + (v[n][2] * v[n][2] + v[n][3] * v[n][3]); }
;                     *(u32x4*)(Yb + blk_off(row, col0 + bj * 128, D_)) = pack8(v[0], v[1]); }
;                 s1 = xsum32(xsum16(s1)); s2 = xsum32(xsum16(s2));
;                 if (fq == 0) *(f32x2*)(stn + (size_t)row * 32 + (u.pn * 4 + wc) * 2) = (f32x2){s1, s2}; asm volatile("" ::: "memory"); } }
	v_pk_fma_f32 v[26:27], v[48:49], v[26:27], v[52:53]
	v_pk_fma_f32 v[28:29], v[46:47], v[28:29], v[50:51]
	v_pk_mul_f32 v[26:27], v[26:27], s[2:3] op_sel_hi:[1,0]
	v_pk_mul_f32 v[28:29], v[28:29], s[2:3] op_sel_hi:[1,0]
	v_pk_fma_f32 v[24:25], v[24:25], 0.5, v[26:27] op_sel_hi:[1,0,1]
	v_pk_fma_f32 v[22:23], v[22:23], 0.5, v[28:29] op_sel_hi:[1,0,1]
	v_add_f32_e32 v27, v24, v25
	v_add_f32_e32 v26, v22, v23
	v_add_f32_e32 v26, v26, v27
	v_add_f32_e32 v31, v31, v26
	v_mul_f32_e32 v26, v23, v23
	v_mul_f32_e32 v27, v25, v25
	v_fmac_f32_e32 v26, v22, v22
	v_fmac_f32_e32 v27, v24, v24
	v_add_f32_e32 v26, v26, v27
	v_add_f32_e32 v30, v30, v26
	v_sub_f32_e32 v27, v37, v59
	v_sub_f32_e32 v26, v36, v59
	v_sub_f32_e32 v29, v35, v59
	v_sub_f32_e32 v28, v34, v59
	v_pk_mul_f32 v[28:29], v[58:59], v[28:29] op_sel_hi:[0,1]
	v_pk_mul_f32 v[26:27], v[58:59], v[26:27] op_sel_hi:[0,1]
	v_pk_fma_f32 v[26:27], v[40:41], v[26:27], v[44:45]
	v_pk_fma_f32 v[28:29], v[38:39], v[28:29], v[42:43]
	v_pk_mul_f32 v[26:27], v[26:27], s[2:3] op_sel_hi:[1,0]
	v_pk_mul_f32 v[28:29], v[28:29], s[2:3] op_sel_hi:[1,0]
	v_pk_fma_f32 v[20:21], v[20:21], 0.5, v[26:27] op_sel_hi:[1,0,1]
	v_pk_fma_f32 v[18:19], v[18:19], 0.5, v[28:29] op_sel_hi:[1,0,1]
	v_add_f32_e32 v27, v20, v21
	v_add_f32_e32 v26, v18, v19
	v_add_f32_e32 v26, v26, v27
	v_mul_f32_e32 v27, v19, v19
	v_mul_f32_e32 v28, v21, v21
	v_add_f32_e32 v26, v31, v26
	v_fmac_f32_e32 v27, v18, v18
	v_fmac_f32_e32 v28, v20, v20
	s_nop 0
	s_nop 1
	v_bfe_u32 v33, v227, 4, 1
	v_sub_u32_e32 v33, 0, v33
	v_lshlrev_b32_e32 v32, 4, v33
	v_lshl_add_u64 v[32:33], v[60:61], 0, v[32:33]
	v_permlane16_swap_b32_e32 v22, v18
	v_permlane16_swap_b32_e32 v23, v19
	v_permlane16_swap_b32_e32 v24, v20
	v_permlane16_swap_b32_e32 v25, v21
	global_store_dwordx4 v[32:33], v[22:25], off offset:512
	global_store_dwordx4 v[32:33], v[18:21], off offset:544
	s_nop 1
	v_permlane16_swap_b32_e32 v22, v18
	v_permlane16_swap_b32_e32 v23, v19
	v_permlane16_swap_b32_e32 v24, v20
	v_permlane16_swap_b32_e32 v25, v21
	v_add_f32_e32 v27, v27, v28
	v_cvt_pk_bf16_f32 v22, v22, v23
	v_cvt_pk_bf16_f32 v23, v24, v25
	v_cvt_pk_bf16_f32 v24, v18, v19
	v_lshl_add_u64 v[18:19], v[78:79], 0, v[0:1]
	v_mov_b32_e32 v0, v26
	v_add_f32_e32 v27, v30, v27
	v_cvt_pk_bf16_f32 v25, v20, v21
	v_permlane16_swap_b32_e32 v26, v0
	global_store_dwordx4 v[18:19], v[22:25], off
	v_add_f32_e32 v18, v26, v0
	v_mov_b32_e32 v0, v27
	s_nop 1
	v_permlane16_swap_b32_e32 v27, v0
	v_add_f32_e32 v19, v27, v0
	v_mov_b32_e32 v20, v18
	v_mov_b32_e32 v21, v19
	s_nop 0
	v_permlane32_swap_b32_e32 v18, v20
	v_permlane32_swap_b32_e32 v19, v21
	s_and_saveexec_b64 s[26:27], s[44:45]
	s_cbranch_execz .LBB0_386
	v_pk_add_f32 v[18:19], v[18:19], v[20:21]
	v_lshlrev_b64 v[20:21], 7, v[76:77]
	v_lshl_add_u64 v[20:21], s[30:31], 0, v[20:21]
	v_lshl_add_u64 v[20:21], s[24:25], 2, v[20:21]
	global_store_dwordx2 v[20:21], v[18:19], off
; __device__ __forceinline__ float xsum16(float v) { const auto r = __builtin_amdgcn_permlane16_swap(__float_as_uint(v), __float_as_uint(v), false, false); return __uint_as_float(r[0]) + __uint_as_float(r[1]); }
; __device__ __forceinline__ float xsum32(float v) { const auto r = __builtin_amdgcn_permlane32_swap(__float_as_uint(v), __float_as_uint(v), false, false); return __uint_as_float(r[0]) + __uint_as_float(r[1]); }
; __device__ __forceinline__ size_t blk_off(int r, int c, int K) { return (size_t)(r >> 8) * 256 * K + (size_t)(c >> 6) * (256 * 64) + (size_t)((r & 255) * 64 + (c & 63)); }
; __device__ __forceinline__ u32x4 pack8(const f32x4 a, const f32x4 b) { u32x4 w; w.x = cvt_pk_bf16(a[0], a[1]); w.y = cvt_pk_bf16(a[2], a[3]); w.z = cvt_pk_bf16(b[0], b[1]); w.w = cvt_pk_bf16(b[2], b[3]); return w; }
;     __device__ __forceinline__ void operator()(const f32x4 (&acc)[2][2][4][2], const pg8::Unit& u, int wr, int wc, int fr, int fq) const {
;     ...
;             for (int m = 0; m < 4; ++m) { const int row = row0 + ai * 128 + m * 16; const float mu = mu4[m], rs = rs4[m];
;                 f32x4 yv[2][2], gq[2][2], bq_[2][2];
; #pragma unroll
;                 for (int bj = 0; bj < 2; ++bj)
; #pragma unroll
;                     for (int n = 0; n < 2; ++n) { yv[bj][n] = *(const f32x4*)(Yin + (size_t)row * D_ + col0 + bj * 128 + 4 * n); gq[bj][n] = *(const f32x4*)(g + col0 + bj * 128 + 4 * n); bq_[bj][n] = *(const f32x4*)(b + col0 + bj * 128 + 4 * n); }
;                 asm volatile("" ::: "memory");
;                 float s1 = 0.f, s2 = 0.f;
; #pragma unroll
;                 for (int bj = 0; bj < 2; ++bj) { float* yp = Y + (size_t)row * D_ + col0 + bj * 128; f32x4 v[2];
; #pragma unroll
;                     for (int n = 0; n < 2; ++n) { v[n] = (((yv[bj][n] - mu) * rs) * gq[bj][n] + bq_[bj][n]) * ALPHA_ + acc[ai][bj][m][n] * sc;
;                         *(f32x4*)(yp + 4 * n) = v[n]; s1 += (v[n][0] + v[n][1]) + (v[n][2] + v[n][3]); s2 += (v[n][0] * v[n][0] + v[n][1] * v[n][1]) + (v[n][2] * v[n][2] + v[n][3] * v[n][3]); }
;                     *(u32x4*)(Yb + blk_off(row, col0 + bj * 128, D_)) = pack8(v[0], v[1]); }
;                 s1 = xsum32(xsum16(s1)); s2 = xsum32(xsum16(s2));
;                 if (fq == 0) *(f32x2*)(stn + (size_t)row * 32 + (u.pn * 4 + wc) * 2) = (f32x2){s1, s2}; asm volatile("" ::: "memory"); } }
.LBB0_386:
	s_or_b64 exec, exec, s[26:27]
	v_lshlrev_b64 v[26:27], 12, v[74:75]
	v_lshl_add_u64 v[18:19], s[12:13], 0, v[26:27]
	v_lshl_add_u64 v[28:29], v[18:19], 0, v[152:153]
	global_load_dwordx4 v[34:37], v[28:29], off
	global_load_dwordx4 v[38:41], v[28:29], off offset:16
	global_load_dwordx4 v[42:45], v[28:29], off offset:512
	global_load_dwordx4 v[46:49], v[156:157], off
	global_load_dwordx4 v[50:53], v[154:155], off
	global_load_dwordx4 v[54:57], v[154:155], off offset:16
	global_load_dwordx4 v[58:61], v[156:157], off offset:16
	global_load_dwordx4 v[62:65], v[154:155], off offset:512
	global_load_dwordx4 v[66:69], v[156:157], off offset:512
	s_load_dwordx16 s[60:75], s[34:35], 0x38
	v_pk_add_f32 v[18:19], v[82:83], v[84:85]
	s_mov_b32 s2, 0x3a800000
	v_pk_mul_f32 v[32:33], v[18:19], s[2:3] op_sel_hi:[1,0]
	global_load_dwordx4 v[18:21], v[154:155], off offset:528
	global_load_dwordx4 v[22:25], v[156:157], off offset:528
	s_waitcnt lgkmcnt(0)
	v_lshl_add_u64 v[26:27], s[74:75], 0, v[26:27]
	v_lshl_add_u64 v[30:31], v[26:27], 0, v[152:153]
	global_load_dwordx4 v[26:29], v[28:29], off offset:528
	v_fma_f32 v32, -v33, v33, v32
	v_lshlrev_b32_e32 v0, 6, v74
	s_movk_i32 s2, 0x3fc0
	v_max_f32_e32 v32, 0, v32
	v_and_or_b32 v0, v0, s2, v194
	v_add_f32_e32 v32, 0x3727c5ac, v32
	s_mov_b32 s2, 0x800000
	v_mul_f32_e32 v70, 0x4b800000, v32
	v_cmp_gt_f32_e32 vcc, s2, v32
	s_mov_b32 s2, 0x3fd744fd
	v_lshlrev_b32_e32 v0, 1, v0
	v_cndmask_b32_e32 v32, v32, v70, vcc
	v_rsq_f32_e32 v32, v32
	v_lshl_add_u64 v[70:71], v[80:81], 0, v[0:1]
	v_mul_f32_e32 v72, 0x45800000, v32
	v_cndmask_b32_e32 v32, v32, v72, vcc
	s_waitcnt vmcnt(11)
	v_sub_f32_e32 v37, v37, v33
	v_sub_f32_e32 v36, v36, v33
	v_sub_f32_e32 v35, v35, v33
	v_sub_f32_e32 v34, v34, v33
	s_waitcnt vmcnt(10)
	v_sub_f32_e32 v41, v41, v33
	v_sub_f32_e32 v40, v40, v33
	v_sub_f32_e32 v39, v39, v33
	v_sub_f32_e32 v38, v38, v33
	v_pk_mul_f32 v[34:35], v[32:33], v[34:35] op_sel_hi:[0,1]
	v_pk_mul_f32 v[36:37], v[32:33], v[36:37] op_sel_hi:[0,1]
	v_pk_mul_f32 v[38:39], v[32:33], v[38:39] op_sel_hi:[0,1]
	v_pk_mul_f32 v[40:41], v[32:33], v[40:41] op_sel_hi:[0,1]
	s_waitcnt vmcnt(7)
	v_pk_fma_f32 v[36:37], v[52:53], v[36:37], v[48:49]
	v_pk_fma_f32 v[34:35], v[50:51], v[34:35], v[46:47]
	s_waitcnt vmcnt(5)
	v_pk_fma_f32 v[40:41], v[56:57], v[40:41], v[60:61]
	v_pk_fma_f32 v[38:39], v[54:55], v[38:39], v[58:59]
	v_pk_mul_f32 v[34:35], v[34:35], s[2:3] op_sel_hi:[1,0]
	v_pk_mul_f32 v[36:37], v[36:37], s[2:3] op_sel_hi:[1,0]
	v_pk_mul_f32 v[38:39], v[38:39], s[2:3] op_sel_hi:[1,0]
	v_pk_mul_f32 v[40:41], v[40:41], s[2:3] op_sel_hi:[1,0]
	v_pk_fma_f32 v[16:17], v[16:17], 0.5, v[36:37] op_sel_hi:[1,0,1]
	v_pk_fma_f32 v[14:15], v[14:15], 0.5, v[34:35] op_sel_hi:[1,0,1]
	v_pk_fma_f32 v[12:13], v[12:13], 0.5, v[40:41] op_sel_hi:[1,0,1]
	v_pk_fma_f32 v[10:11], v[10:11], 0.5, v[38:39] op_sel_hi:[1,0,1]
	v_sub_f32_e32 v45, v45, v33
	v_sub_f32_e32 v44, v44, v33
	v_sub_f32_e32 v43, v43, v33
	v_sub_f32_e32 v42, v42, v33
	v_add_f32_e32 v38, v14, v15
	v_add_f32_e32 v39, v16, v17
	v_mul_f32_e32 v40, v15, v15
	v_mul_f32_e32 v41, v17, v17
	v_mul_f32_e32 v48, v11, v11
	v_mul_f32_e32 v49, v13, v13
	v_pk_mul_f32 v[42:43], v[32:33], v[42:43] op_sel_hi:[0,1]
	v_pk_mul_f32 v[44:45], v[32:33], v[44:45] op_sel_hi:[0,1]
	global_store_dwordx4 v[30:31], v[10:13], off offset:16
	v_add_f32_e32 v46, v10, v11
	v_add_f32_e32 v47, v12, v13
	v_cvt_pk_bf16_f32 v36, v10, v11
	v_add_f32_e32 v11, v38, v39
	v_fmac_f32_e32 v40, v14, v14
	v_fmac_f32_e32 v41, v16, v16
	v_fmac_f32_e32 v48, v10, v10
	v_fmac_f32_e32 v49, v12, v12
	s_waitcnt vmcnt(4)
	v_pk_fma_f32 v[44:45], v[64:65], v[44:45], v[68:69]
	v_pk_fma_f32 v[42:43], v[62:63], v[42:43], v[66:67]
	v_cvt_pk_bf16_f32 v37, v12, v13
	v_add_f32_e32 v13, v46, v47
	v_add_f32_e32 v10, 0, v11
	v_add_f32_e32 v11, v40, v41
	v_add_f32_e32 v12, v48, v49
	global_store_dwordx4 v[30:31], v[14:17], off
	v_cvt_pk_bf16_f32 v34, v14, v15
	v_cvt_pk_bf16_f32 v35, v16, v17
	v_add_f32_e32 v14, v10, v13
	v_add_f32_e32 v15, v11, v12
	v_pk_mul_f32 v[10:11], v[42:43], s[2:3] op_sel_hi:[1,0]
	v_pk_mul_f32 v[12:13], v[44:45], s[2:3] op_sel_hi:[1,0]
	v_pk_fma_f32 v[6:7], v[6:7], 0.5, v[10:11] op_sel_hi:[1,0,1]
	v_pk_fma_f32 v[8:9], v[8:9], 0.5, v[12:13] op_sel_hi:[1,0,1]
	v_add_f32_e32 v10, v6, v7
	v_add_f32_e32 v11, v8, v9
	v_add_f32_e32 v10, v10, v11
	v_add_f32_e32 v14, v14, v10
	v_mul_f32_e32 v10, v7, v7
	v_mul_f32_e32 v11, v9, v9
	v_fmac_f32_e32 v10, v6, v6
	v_fmac_f32_e32 v11, v8, v8
	v_add_f32_e32 v10, v10, v11
	v_add_f32_e32 v15, v15, v10
	s_waitcnt vmcnt(2)
	v_sub_f32_e32 v11, v29, v33
	v_sub_f32_e32 v10, v28, v33
	v_sub_f32_e32 v13, v27, v33
	v_sub_f32_e32 v12, v26, v33
	v_pk_mul_f32 v[12:13], v[32:33], v[12:13] op_sel_hi:[0,1]
	v_pk_mul_f32 v[10:11], v[32:33], v[10:11] op_sel_hi:[0,1]
	v_pk_fma_f32 v[10:11], v[20:21], v[10:11], v[24:25]
	v_pk_fma_f32 v[12:13], v[18:19], v[12:13], v[22:23]
	v_pk_mul_f32 v[10:11], v[10:11], s[2:3] op_sel_hi:[1,0]
	v_pk_mul_f32 v[12:13], v[12:13], s[2:3] op_sel_hi:[1,0]
	v_pk_fma_f32 v[4:5], v[4:5], 0.5, v[10:11] op_sel_hi:[1,0,1]
	v_pk_fma_f32 v[2:3], v[2:3], 0.5, v[12:13] op_sel_hi:[1,0,1]
	v_add_f32_e32 v11, v4, v5
	v_add_f32_e32 v10, v2, v3
	v_add_f32_e32 v10, v10, v11
	v_mul_f32_e32 v11, v3, v3
	v_mul_f32_e32 v12, v5, v5
	v_add_f32_e32 v10, v14, v10
	v_fmac_f32_e32 v11, v2, v2
	v_fmac_f32_e32 v12, v4, v4
	global_store_dwordx4 v[70:71], v[34:37], off
	s_nop 0
	s_nop 1
	v_bfe_u32 v17, v227, 4, 1
	v_sub_u32_e32 v17, 0, v17
	v_lshlrev_b32_e32 v16, 4, v17
	v_lshl_add_u64 v[16:17], v[30:31], 0, v[16:17]
	v_permlane16_swap_b32_e32 v6, v2
	v_permlane16_swap_b32_e32 v7, v3
	v_permlane16_swap_b32_e32 v8, v4
	v_permlane16_swap_b32_e32 v9, v5
	global_store_dwordx4 v[16:17], v[6:9], off offset:512
	global_store_dwordx4 v[16:17], v[2:5], off offset:544
	s_nop 1
	v_permlane16_swap_b32_e32 v6, v2
	v_permlane16_swap_b32_e32 v7, v3
	v_permlane16_swap_b32_e32 v8, v4
	v_permlane16_swap_b32_e32 v9, v5
	v_add_f32_e32 v11, v11, v12
	v_cvt_pk_bf16_f32 v6, v6, v7
	v_cvt_pk_bf16_f32 v7, v8, v9
	v_cvt_pk_bf16_f32 v8, v2, v3
	v_lshl_add_u64 v[2:3], v[78:79], 0, v[0:1]
	v_mov_b32_e32 v0, v10
	v_add_f32_e32 v11, v15, v11
	v_cvt_pk_bf16_f32 v9, v4, v5
	v_permlane16_swap_b32_e32 v10, v0
	global_store_dwordx4 v[2:3], v[6:9], off
	v_add_f32_e32 v2, v10, v0
	v_mov_b32_e32 v0, v11
	s_nop 1
	v_permlane16_swap_b32_e32 v11, v0
	v_add_f32_e32 v3, v11, v0
	v_mov_b32_e32 v4, v2
	v_mov_b32_e32 v5, v3
	s_nop 0
	v_permlane32_swap_b32_e32 v2, v4
	v_permlane32_swap_b32_e32 v3, v5
	s_and_saveexec_b64 s[26:27], s[44:45]
	s_cbranch_execz .LBB0_388
	v_pk_add_f32 v[2:3], v[2:3], v[4:5]
	v_lshlrev_b64 v[4:5], 7, v[74:75]
	v_lshl_add_u64 v[4:5], s[30:31], 0, v[4:5]
	v_lshl_add_u64 v[4:5], s[24:25], 2, v[4:5]
	global_store_dwordx2 v[4:5], v[2:3], off
